# K-loop: removed the mid-segment s_setprio 0/1 flip pairs (prio stays 1 across each 32-MFMA segment)
# speedup vs baseline: 1.0010x; 1.0004x over previous
.LBB0_389:
	s_ashr_i32 s29, s28, 31
	s_lshl_b64 s[4:5], s[28:29], 19
	s_add_u32 s30, s12, s4
	s_addc_u32 s31, s13, s5
	s_and_b64 s[4:5], s[40:41], exec
	s_cselect_b32 s29, s31, s43
	s_cselect_b32 vcc_lo, s30, s42
	s_ashr_i32 s37, s36, 31
	s_lshl_b64 s[4:5], s[36:37], 19
	s_add_u32 s34, s17, s4
	s_addc_u32 s35, s70, s5
	s_and_b64 s[4:5], s[40:41], exec
	s_cselect_b32 s37, s35, s39
	s_cselect_b32 vcc_hi, s34, s38
	s_add_u32 s59, s38, 0x100
	v_mov_b32_e32 v74, 0
	s_addc_u32 s72, s39, 0
	s_mov_b32 s73, -2
	s_add_u32 s38, s42, 0x100
	s_addc_u32 s39, s43, 0
	s_add_i32 s4, 0, 0x10000
	s_cmp_eq_u32 s73, 12
	s_cselect_b32 s69, s29, s39
	s_cselect_b32 s68, vcc_lo, s38
	s_cselect_b32 s67, s37, s72
	s_cselect_b32 s66, vcc_hi, s59
	s_add_i32 s6, 0, 0x14000
	v_add_u32_e32 v142, s4, v251
	v_add_u32_e32 v158, s6, v251
	ds_read_b128 v[130:133], v142
	ds_read_b128 v[134:137], v142 offset:1024
	ds_read_b128 v[138:141], v142 offset:2048
	ds_read_b128 v[142:145], v142 offset:3072
	ds_read_b128 v[146:149], v158
	ds_read_b128 v[150:153], v158 offset:1024
	ds_read_b128 v[154:157], v158 offset:2048
	ds_read_b128 v[158:161], v158 offset:3072
	v_lshl_add_u64 v[194:195], s[42:43], 0, v[228:229]
	s_add_i32 m0, s75, 0xc000
	ds_read_b128 v[162:165], v244
	ds_read_b128 v[166:169], v244 offset:1024
	ds_read_b128 v[170:173], v244 offset:2048
	ds_read_b128 v[174:177], v244 offset:3072
	ds_read_b128 v[178:181], v244 offset:4096
	ds_read_b128 v[182:185], v244 offset:5120
	ds_read_b128 v[186:189], v244 offset:6144
	ds_read_b128 v[190:193], v244 offset:7168
	global_load_lds_dwordx4 v[194:195], off
	v_lshl_add_u64 v[194:195], s[42:43], 0, v[230:231]
	s_add_i32 m0, s75, 0xe000
	s_nop 0
	global_load_lds_dwordx4 v[194:195], off
	s_waitcnt vmcnt(8)
	s_waitcnt lgkmcnt(0)
	s_barrier
	s_setprio 1
	s_waitcnt lgkmcnt(0)
	v_mfma_f32_16x16x32_bf16 v[114:117], v[130:133], v[162:165], 0
	v_mfma_f32_16x16x32_bf16 v[122:125], v[138:141], v[162:165], 0
	v_mfma_f32_16x16x32_bf16 v[118:121], v[130:133], v[170:173], 0
	v_mfma_f32_16x16x32_bf16 v[126:129], v[138:141], v[170:173], 0
	v_mfma_f32_16x16x32_bf16 v[54:57], v[130:133], v[178:181], 0
	v_mfma_f32_16x16x32_bf16 v[70:73], v[138:141], v[178:181], 0
	v_mfma_f32_16x16x32_bf16 v[50:53], v[130:133], v[186:189], 0
	v_mfma_f32_16x16x32_bf16 v[66:69], v[138:141], v[186:189], 0
	v_mfma_f32_16x16x32_bf16 v[114:117], v[134:137], v[166:169], v[114:117]
	v_mfma_f32_16x16x32_bf16 v[122:125], v[142:145], v[166:169], v[122:125]
	v_mfma_f32_16x16x32_bf16 v[118:121], v[134:137], v[174:177], v[118:121]
	v_mfma_f32_16x16x32_bf16 v[126:129], v[142:145], v[174:177], v[126:129]
	v_mfma_f32_16x16x32_bf16 v[54:57], v[134:137], v[182:185], v[54:57]
	v_mfma_f32_16x16x32_bf16 v[70:73], v[142:145], v[182:185], v[70:73]
	v_mfma_f32_16x16x32_bf16 v[50:53], v[134:137], v[190:193], v[50:53]
	v_mfma_f32_16x16x32_bf16 v[66:69], v[142:145], v[190:193], v[66:69]
	v_mfma_f32_16x16x32_bf16 v[106:109], v[146:149], v[162:165], 0
	v_mfma_f32_16x16x32_bf16 v[42:45], v[154:157], v[162:165], 0
	v_mfma_f32_16x16x32_bf16 v[110:113], v[146:149], v[170:173], 0
	v_mfma_f32_16x16x32_bf16 v[46:49], v[154:157], v[170:173], 0
	v_mfma_f32_16x16x32_bf16 v[30:33], v[146:149], v[178:181], 0
	v_mfma_f32_16x16x32_bf16 v[14:17], v[154:157], v[178:181], 0
	v_mfma_f32_16x16x32_bf16 v[26:29], v[146:149], v[186:189], 0
	v_mfma_f32_16x16x32_bf16 v[10:13], v[154:157], v[186:189], 0
	v_mfma_f32_16x16x32_bf16 v[106:109], v[150:153], v[166:169], v[106:109]
	v_mfma_f32_16x16x32_bf16 v[42:45], v[158:161], v[166:169], v[42:45]
	v_mfma_f32_16x16x32_bf16 v[110:113], v[150:153], v[174:177], v[110:113]
	v_mfma_f32_16x16x32_bf16 v[46:49], v[158:161], v[174:177], v[46:49]
	v_mfma_f32_16x16x32_bf16 v[30:33], v[150:153], v[182:185], v[30:33]
	v_mfma_f32_16x16x32_bf16 v[14:17], v[158:161], v[182:185], v[14:17]
	v_mfma_f32_16x16x32_bf16 v[26:29], v[150:153], v[190:193], v[26:29]
	s_barrier
	v_mfma_f32_16x16x32_bf16 v[10:13], v[158:161], v[190:193], v[10:13]
	s_setprio 0
	s_add_i32 s4, s4, s74
	v_lshl_add_u64 v[194:195], s[66:67], 0, v[0:1]
	s_mov_b32 m0, s4
	ds_read_b128 v[162:165], v244 offset:16384
	ds_read_b128 v[166:169], v244 offset:17408
	ds_read_b128 v[170:173], v244 offset:18432
	ds_read_b128 v[174:177], v244 offset:19456
	ds_read_b128 v[178:181], v244 offset:20480
	ds_read_b128 v[182:185], v244 offset:21504
	ds_read_b128 v[186:189], v244 offset:22528
	ds_read_b128 v[190:193], v244 offset:23552
	global_load_lds_dwordx4 v[194:195], off
	s_add_i32 m0, s4, 0x2000
	s_add_u32 s4, s66, 0x40000
	v_lshl_add_u64 v[196:197], s[66:67], 0, v[224:225]
	s_addc_u32 s5, s67, 0
	s_add_i32 s6, s6, s74
	global_load_lds_dwordx4 v[196:197], off
	v_lshl_add_u64 v[198:199], s[4:5], 0, v[0:1]
	s_mov_b32 m0, s6
	v_lshl_add_u64 v[200:201], s[68:69], 0, v[222:223]
	global_load_lds_dwordx4 v[198:199], off
	v_lshl_add_u64 v[198:199], s[4:5], 0, v[224:225]
	s_add_i32 m0, s6, 0x2000
	s_nop 0
	global_load_lds_dwordx4 v[198:199], off
	v_lshl_add_u64 v[198:199], s[68:69], 0, v[226:227]
	s_mov_b32 m0, s75
	s_nop 0
	global_load_lds_dwordx4 v[198:199], off
	s_mov_b32 m0, s76
	s_nop 0
	global_load_lds_dwordx4 v[200:201], off
	s_waitcnt vmcnt(8)
	s_waitcnt lgkmcnt(0)
	s_barrier
	s_setprio 1
	s_waitcnt lgkmcnt(0)
	v_mfma_f32_16x16x32_bf16 v[38:41], v[130:133], v[162:165], 0
	v_mfma_f32_16x16x32_bf16 v[62:65], v[138:141], v[162:165], 0
	v_mfma_f32_16x16x32_bf16 v[34:37], v[130:133], v[170:173], 0
	v_mfma_f32_16x16x32_bf16 v[58:61], v[138:141], v[170:173], 0
	v_mfma_f32_16x16x32_bf16 v[102:105], v[130:133], v[178:181], 0
	v_mfma_f32_16x16x32_bf16 v[98:101], v[138:141], v[178:181], 0
	v_mfma_f32_16x16x32_bf16 v[94:97], v[130:133], v[186:189], 0
	v_mfma_f32_16x16x32_bf16 v[90:93], v[138:141], v[186:189], 0
	v_mfma_f32_16x16x32_bf16 v[38:41], v[134:137], v[166:169], v[38:41]
	v_mfma_f32_16x16x32_bf16 v[62:65], v[142:145], v[166:169], v[62:65]
	v_mfma_f32_16x16x32_bf16 v[34:37], v[134:137], v[174:177], v[34:37]
	v_mfma_f32_16x16x32_bf16 v[58:61], v[142:145], v[174:177], v[58:61]
	v_mfma_f32_16x16x32_bf16 v[102:105], v[134:137], v[182:185], v[102:105]
	v_mfma_f32_16x16x32_bf16 v[98:101], v[142:145], v[182:185], v[98:101]
	v_mfma_f32_16x16x32_bf16 v[94:97], v[134:137], v[190:193], v[94:97]
	v_mfma_f32_16x16x32_bf16 v[90:93], v[142:145], v[190:193], v[90:93]
	v_mfma_f32_16x16x32_bf16 v[22:25], v[146:149], v[162:165], 0
	v_mfma_f32_16x16x32_bf16 v[6:9], v[154:157], v[162:165], 0
	v_mfma_f32_16x16x32_bf16 v[18:21], v[146:149], v[170:173], 0
	v_mfma_f32_16x16x32_bf16 v[2:5], v[154:157], v[170:173], 0
	v_mfma_f32_16x16x32_bf16 v[86:89], v[146:149], v[178:181], 0
	v_mfma_f32_16x16x32_bf16 v[82:85], v[154:157], v[178:181], 0
	v_mfma_f32_16x16x32_bf16 v[78:81], v[146:149], v[186:189], 0
	v_mfma_f32_16x16x32_bf16 v[74:77], v[154:157], v[186:189], 0
	v_mfma_f32_16x16x32_bf16 v[22:25], v[150:153], v[166:169], v[22:25]
	v_mfma_f32_16x16x32_bf16 v[6:9], v[158:161], v[166:169], v[6:9]
	v_mfma_f32_16x16x32_bf16 v[18:21], v[150:153], v[174:177], v[18:21]
	v_mfma_f32_16x16x32_bf16 v[2:5], v[158:161], v[174:177], v[2:5]
	v_mfma_f32_16x16x32_bf16 v[86:89], v[150:153], v[182:185], v[86:89]
	v_mfma_f32_16x16x32_bf16 v[82:85], v[158:161], v[182:185], v[82:85]
	v_mfma_f32_16x16x32_bf16 v[78:81], v[150:153], v[190:193], v[78:81]
	s_barrier
	v_mfma_f32_16x16x32_bf16 v[74:77], v[158:161], v[190:193], v[74:77]
	s_setprio 0
	s_add_i32 s6, 0, 0x18000
	s_add_i32 s7, 0, 0x1c000
	v_add_u32_e32 v142, s6, v251
	v_add_u32_e32 v158, s7, v251
	ds_read_b128 v[130:133], v142
	ds_read_b128 v[134:137], v142 offset:1024
	ds_read_b128 v[138:141], v142 offset:2048
	ds_read_b128 v[142:145], v142 offset:3072
	ds_read_b128 v[146:149], v158
	ds_read_b128 v[150:153], v158 offset:1024
	ds_read_b128 v[154:157], v158 offset:2048
	ds_read_b128 v[158:161], v158 offset:3072
	s_add_u32 s4, s68, 0x2000
	s_addc_u32 s5, s69, 0
	s_mov_b32 m0, s77
	v_lshl_add_u64 v[202:203], s[4:5], 0, v[226:227]
	ds_read_b128 v[162:165], v244 offset:32768
	ds_read_b128 v[166:169], v244 offset:33792
	ds_read_b128 v[170:173], v244 offset:34816
	ds_read_b128 v[174:177], v244 offset:35840
	ds_read_b128 v[178:181], v244 offset:36864
	ds_read_b128 v[182:185], v244 offset:37888
	ds_read_b128 v[186:189], v244 offset:38912
	ds_read_b128 v[190:193], v244 offset:39936
	global_load_lds_dwordx4 v[202:203], off
	v_lshl_add_u64 v[202:203], s[4:5], 0, v[222:223]
	s_mov_b32 m0, s78
	s_nop 0
	global_load_lds_dwordx4 v[202:203], off
	s_waitcnt vmcnt(8)
	s_waitcnt lgkmcnt(0)
	s_barrier
	s_setprio 1
	s_waitcnt lgkmcnt(0)
	v_mfma_f32_16x16x32_bf16 v[114:117], v[130:133], v[162:165], v[114:117]
	v_mfma_f32_16x16x32_bf16 v[122:125], v[138:141], v[162:165], v[122:125]
	v_mfma_f32_16x16x32_bf16 v[118:121], v[130:133], v[170:173], v[118:121]
	v_mfma_f32_16x16x32_bf16 v[126:129], v[138:141], v[170:173], v[126:129]
	v_mfma_f32_16x16x32_bf16 v[54:57], v[130:133], v[178:181], v[54:57]
	v_mfma_f32_16x16x32_bf16 v[70:73], v[138:141], v[178:181], v[70:73]
	v_mfma_f32_16x16x32_bf16 v[50:53], v[130:133], v[186:189], v[50:53]
	v_mfma_f32_16x16x32_bf16 v[66:69], v[138:141], v[186:189], v[66:69]
	v_mfma_f32_16x16x32_bf16 v[114:117], v[134:137], v[166:169], v[114:117]
	v_mfma_f32_16x16x32_bf16 v[122:125], v[142:145], v[166:169], v[122:125]
	v_mfma_f32_16x16x32_bf16 v[118:121], v[134:137], v[174:177], v[118:121]
	v_mfma_f32_16x16x32_bf16 v[126:129], v[142:145], v[174:177], v[126:129]
	v_mfma_f32_16x16x32_bf16 v[54:57], v[134:137], v[182:185], v[54:57]
	v_mfma_f32_16x16x32_bf16 v[70:73], v[142:145], v[182:185], v[70:73]
	v_mfma_f32_16x16x32_bf16 v[50:53], v[134:137], v[190:193], v[50:53]
	v_mfma_f32_16x16x32_bf16 v[66:69], v[142:145], v[190:193], v[66:69]
	v_mfma_f32_16x16x32_bf16 v[106:109], v[146:149], v[162:165], v[106:109]
	v_mfma_f32_16x16x32_bf16 v[42:45], v[154:157], v[162:165], v[42:45]
	v_mfma_f32_16x16x32_bf16 v[110:113], v[146:149], v[170:173], v[110:113]
	v_mfma_f32_16x16x32_bf16 v[46:49], v[154:157], v[170:173], v[46:49]
	v_mfma_f32_16x16x32_bf16 v[30:33], v[146:149], v[178:181], v[30:33]
	v_mfma_f32_16x16x32_bf16 v[14:17], v[154:157], v[178:181], v[14:17]
	v_mfma_f32_16x16x32_bf16 v[26:29], v[146:149], v[186:189], v[26:29]
	v_mfma_f32_16x16x32_bf16 v[10:13], v[154:157], v[186:189], v[10:13]
	v_mfma_f32_16x16x32_bf16 v[106:109], v[150:153], v[166:169], v[106:109]
	v_mfma_f32_16x16x32_bf16 v[42:45], v[158:161], v[166:169], v[42:45]
	v_mfma_f32_16x16x32_bf16 v[110:113], v[150:153], v[174:177], v[110:113]
	v_mfma_f32_16x16x32_bf16 v[46:49], v[158:161], v[174:177], v[46:49]
	v_mfma_f32_16x16x32_bf16 v[30:33], v[150:153], v[182:185], v[30:33]
	v_mfma_f32_16x16x32_bf16 v[14:17], v[158:161], v[182:185], v[14:17]
	v_mfma_f32_16x16x32_bf16 v[26:29], v[150:153], v[190:193], v[26:29]
	s_barrier
	v_mfma_f32_16x16x32_bf16 v[10:13], v[158:161], v[190:193], v[10:13]
	s_setprio 0
	s_add_i32 s4, s6, s74
	v_lshl_add_u64 v[194:195], v[194:195], 0, s[82:83]
	s_mov_b32 m0, s4
	ds_read_b128 v[162:165], v244 offset:49152
	ds_read_b128 v[166:169], v244 offset:50176
	ds_read_b128 v[170:173], v244 offset:51200
	ds_read_b128 v[174:177], v244 offset:52224
	ds_read_b128 v[178:181], v244 offset:53248
	ds_read_b128 v[182:185], v244 offset:54272
	ds_read_b128 v[186:189], v244 offset:55296
	ds_read_b128 v[190:193], v244 offset:56320
	global_load_lds_dwordx4 v[194:195], off
	s_add_i32 m0, s4, 0x2000
	s_add_u32 s4, s66, 0x40080
	v_lshl_add_u64 v[194:195], v[196:197], 0, s[82:83]
	s_addc_u32 s5, s67, 0
	s_add_i32 s6, s7, s74
	global_load_lds_dwordx4 v[194:195], off
	v_lshl_add_u64 v[194:195], s[4:5], 0, v[0:1]
	s_mov_b32 m0, s6
	s_nop 0
	global_load_lds_dwordx4 v[194:195], off
	v_lshl_add_u64 v[194:195], s[4:5], 0, v[224:225]
	s_add_i32 m0, s6, 0x2000
	s_nop 0
	global_load_lds_dwordx4 v[194:195], off
	v_lshl_add_u64 v[194:195], v[198:199], 0, s[82:83]
	s_mov_b32 m0, s94
	s_nop 0
	global_load_lds_dwordx4 v[194:195], off
	v_lshl_add_u64 v[194:195], v[200:201], 0, s[82:83]
	s_mov_b32 m0, s95
	s_nop 0
	global_load_lds_dwordx4 v[194:195], off
	s_waitcnt vmcnt(8)
	s_waitcnt lgkmcnt(0)
	s_barrier
	s_setprio 1
	s_waitcnt lgkmcnt(0)
	v_mfma_f32_16x16x32_bf16 v[38:41], v[130:133], v[162:165], v[38:41]
	v_mfma_f32_16x16x32_bf16 v[62:65], v[138:141], v[162:165], v[62:65]
	v_mfma_f32_16x16x32_bf16 v[34:37], v[130:133], v[170:173], v[34:37]
	v_mfma_f32_16x16x32_bf16 v[58:61], v[138:141], v[170:173], v[58:61]
	v_mfma_f32_16x16x32_bf16 v[102:105], v[130:133], v[178:181], v[102:105]
	v_mfma_f32_16x16x32_bf16 v[98:101], v[138:141], v[178:181], v[98:101]
	v_mfma_f32_16x16x32_bf16 v[94:97], v[130:133], v[186:189], v[94:97]
	v_mfma_f32_16x16x32_bf16 v[90:93], v[138:141], v[186:189], v[90:93]
	v_mfma_f32_16x16x32_bf16 v[38:41], v[134:137], v[166:169], v[38:41]
	v_mfma_f32_16x16x32_bf16 v[62:65], v[142:145], v[166:169], v[62:65]
	v_mfma_f32_16x16x32_bf16 v[34:37], v[134:137], v[174:177], v[34:37]
	v_mfma_f32_16x16x32_bf16 v[58:61], v[142:145], v[174:177], v[58:61]
	v_mfma_f32_16x16x32_bf16 v[102:105], v[134:137], v[182:185], v[102:105]
	v_mfma_f32_16x16x32_bf16 v[98:101], v[142:145], v[182:185], v[98:101]
	v_mfma_f32_16x16x32_bf16 v[94:97], v[134:137], v[190:193], v[94:97]
	v_mfma_f32_16x16x32_bf16 v[90:93], v[142:145], v[190:193], v[90:93]
	v_mfma_f32_16x16x32_bf16 v[22:25], v[146:149], v[162:165], v[22:25]
	v_mfma_f32_16x16x32_bf16 v[6:9], v[154:157], v[162:165], v[6:9]
	v_mfma_f32_16x16x32_bf16 v[18:21], v[146:149], v[170:173], v[18:21]
	v_mfma_f32_16x16x32_bf16 v[2:5], v[154:157], v[170:173], v[2:5]
	v_mfma_f32_16x16x32_bf16 v[86:89], v[146:149], v[178:181], v[86:89]
	v_mfma_f32_16x16x32_bf16 v[82:85], v[154:157], v[178:181], v[82:85]
	v_mfma_f32_16x16x32_bf16 v[78:81], v[146:149], v[186:189], v[78:81]
	v_mfma_f32_16x16x32_bf16 v[74:77], v[154:157], v[186:189], v[74:77]
	v_mfma_f32_16x16x32_bf16 v[22:25], v[150:153], v[166:169], v[22:25]
	v_mfma_f32_16x16x32_bf16 v[6:9], v[158:161], v[166:169], v[6:9]
	v_mfma_f32_16x16x32_bf16 v[18:21], v[150:153], v[174:177], v[18:21]
	v_mfma_f32_16x16x32_bf16 v[2:5], v[158:161], v[174:177], v[2:5]
	v_mfma_f32_16x16x32_bf16 v[86:89], v[150:153], v[182:185], v[86:89]
	v_mfma_f32_16x16x32_bf16 v[82:85], v[158:161], v[182:185], v[82:85]
	v_mfma_f32_16x16x32_bf16 v[78:81], v[150:153], v[190:193], v[78:81]
	s_barrier
	v_mfma_f32_16x16x32_bf16 v[74:77], v[158:161], v[190:193], v[74:77]
	s_setprio 0
	s_add_i32 s73, s73, 2
	s_add_u32 s59, s59, 0x100
	s_addc_u32 s72, s72, 0
	s_cmp_gt_u32 s73, 13
	s_mov_b64 s[42:43], s[38:39]
.LBB0_390:
	s_add_u32 s38, s42, 0x100
	s_addc_u32 s39, s43, 0
	s_add_i32 s4, 0, 0x10000
	s_cmp_eq_u32 s73, 12
	s_cselect_b32 s69, s29, s39
	s_cselect_b32 s68, vcc_lo, s38
	s_cselect_b32 s67, s37, s72
	s_cselect_b32 s66, vcc_hi, s59
	s_add_i32 s6, 0, 0x14000
	v_add_u32_e32 v142, s4, v251
	v_add_u32_e32 v158, s6, v251
	ds_read_b128 v[130:133], v142
	ds_read_b128 v[134:137], v142 offset:1024
	ds_read_b128 v[138:141], v142 offset:2048
	ds_read_b128 v[142:145], v142 offset:3072
	ds_read_b128 v[146:149], v158
	ds_read_b128 v[150:153], v158 offset:1024
	ds_read_b128 v[154:157], v158 offset:2048
	ds_read_b128 v[158:161], v158 offset:3072
	v_lshl_add_u64 v[194:195], s[42:43], 0, v[228:229]
	s_add_i32 m0, s75, 0xc000
	ds_read_b128 v[162:165], v244
	ds_read_b128 v[166:169], v244 offset:1024
	ds_read_b128 v[170:173], v244 offset:2048
	ds_read_b128 v[174:177], v244 offset:3072
	ds_read_b128 v[178:181], v244 offset:4096
	ds_read_b128 v[182:185], v244 offset:5120
	ds_read_b128 v[186:189], v244 offset:6144
	ds_read_b128 v[190:193], v244 offset:7168
	global_load_lds_dwordx4 v[194:195], off
	v_lshl_add_u64 v[194:195], s[42:43], 0, v[230:231]
	s_add_i32 m0, s75, 0xe000
	s_nop 0
	global_load_lds_dwordx4 v[194:195], off
	s_waitcnt vmcnt(8)
	s_waitcnt lgkmcnt(0)
	s_barrier
	s_setprio 1
	s_waitcnt lgkmcnt(0)
	v_mfma_f32_16x16x32_bf16 v[114:117], v[130:133], v[162:165], v[114:117]
	v_mfma_f32_16x16x32_bf16 v[122:125], v[138:141], v[162:165], v[122:125]
	v_mfma_f32_16x16x32_bf16 v[118:121], v[130:133], v[170:173], v[118:121]
	v_mfma_f32_16x16x32_bf16 v[126:129], v[138:141], v[170:173], v[126:129]
	v_mfma_f32_16x16x32_bf16 v[54:57], v[130:133], v[178:181], v[54:57]
	v_mfma_f32_16x16x32_bf16 v[70:73], v[138:141], v[178:181], v[70:73]
	v_mfma_f32_16x16x32_bf16 v[50:53], v[130:133], v[186:189], v[50:53]
	v_mfma_f32_16x16x32_bf16 v[66:69], v[138:141], v[186:189], v[66:69]
	v_mfma_f32_16x16x32_bf16 v[114:117], v[134:137], v[166:169], v[114:117]
	v_mfma_f32_16x16x32_bf16 v[122:125], v[142:145], v[166:169], v[122:125]
	v_mfma_f32_16x16x32_bf16 v[118:121], v[134:137], v[174:177], v[118:121]
	v_mfma_f32_16x16x32_bf16 v[126:129], v[142:145], v[174:177], v[126:129]
	v_mfma_f32_16x16x32_bf16 v[54:57], v[134:137], v[182:185], v[54:57]
	v_mfma_f32_16x16x32_bf16 v[70:73], v[142:145], v[182:185], v[70:73]
	v_mfma_f32_16x16x32_bf16 v[50:53], v[134:137], v[190:193], v[50:53]
	v_mfma_f32_16x16x32_bf16 v[66:69], v[142:145], v[190:193], v[66:69]
	v_mfma_f32_16x16x32_bf16 v[106:109], v[146:149], v[162:165], v[106:109]
	v_mfma_f32_16x16x32_bf16 v[42:45], v[154:157], v[162:165], v[42:45]
	v_mfma_f32_16x16x32_bf16 v[110:113], v[146:149], v[170:173], v[110:113]
	v_mfma_f32_16x16x32_bf16 v[46:49], v[154:157], v[170:173], v[46:49]
	v_mfma_f32_16x16x32_bf16 v[30:33], v[146:149], v[178:181], v[30:33]
	v_mfma_f32_16x16x32_bf16 v[14:17], v[154:157], v[178:181], v[14:17]
	v_mfma_f32_16x16x32_bf16 v[26:29], v[146:149], v[186:189], v[26:29]
	v_mfma_f32_16x16x32_bf16 v[10:13], v[154:157], v[186:189], v[10:13]
	v_mfma_f32_16x16x32_bf16 v[106:109], v[150:153], v[166:169], v[106:109]
	v_mfma_f32_16x16x32_bf16 v[42:45], v[158:161], v[166:169], v[42:45]
	v_mfma_f32_16x16x32_bf16 v[110:113], v[150:153], v[174:177], v[110:113]
	v_mfma_f32_16x16x32_bf16 v[46:49], v[158:161], v[174:177], v[46:49]
	v_mfma_f32_16x16x32_bf16 v[30:33], v[150:153], v[182:185], v[30:33]
	v_mfma_f32_16x16x32_bf16 v[14:17], v[158:161], v[182:185], v[14:17]
	v_mfma_f32_16x16x32_bf16 v[26:29], v[150:153], v[190:193], v[26:29]
	s_barrier
	v_mfma_f32_16x16x32_bf16 v[10:13], v[158:161], v[190:193], v[10:13]
	s_setprio 0
	s_add_i32 s4, s4, s74
	v_lshl_add_u64 v[194:195], s[66:67], 0, v[0:1]
	s_mov_b32 m0, s4
	ds_read_b128 v[162:165], v244 offset:16384
	ds_read_b128 v[166:169], v244 offset:17408
	ds_read_b128 v[170:173], v244 offset:18432
	ds_read_b128 v[174:177], v244 offset:19456
	ds_read_b128 v[178:181], v244 offset:20480
	ds_read_b128 v[182:185], v244 offset:21504
	ds_read_b128 v[186:189], v244 offset:22528
	ds_read_b128 v[190:193], v244 offset:23552
	global_load_lds_dwordx4 v[194:195], off
	s_add_i32 m0, s4, 0x2000
	s_add_u32 s4, s66, 0x40000
	v_lshl_add_u64 v[196:197], s[66:67], 0, v[224:225]
	s_addc_u32 s5, s67, 0
	s_add_i32 s6, s6, s74
	global_load_lds_dwordx4 v[196:197], off
	v_lshl_add_u64 v[198:199], s[4:5], 0, v[0:1]
	s_mov_b32 m0, s6
	v_lshl_add_u64 v[200:201], s[68:69], 0, v[222:223]
	global_load_lds_dwordx4 v[198:199], off
	v_lshl_add_u64 v[198:199], s[4:5], 0, v[224:225]
	s_add_i32 m0, s6, 0x2000
	s_nop 0
	global_load_lds_dwordx4 v[198:199], off
	v_lshl_add_u64 v[198:199], s[68:69], 0, v[226:227]
	s_mov_b32 m0, s75
	s_nop 0
	global_load_lds_dwordx4 v[198:199], off
	s_mov_b32 m0, s76
	s_nop 0
	global_load_lds_dwordx4 v[200:201], off
	s_waitcnt vmcnt(8)
	s_waitcnt lgkmcnt(0)
	s_barrier
	s_setprio 1
	s_waitcnt lgkmcnt(0)
	v_mfma_f32_16x16x32_bf16 v[38:41], v[130:133], v[162:165], v[38:41]
	v_mfma_f32_16x16x32_bf16 v[62:65], v[138:141], v[162:165], v[62:65]
	v_mfma_f32_16x16x32_bf16 v[34:37], v[130:133], v[170:173], v[34:37]
	v_mfma_f32_16x16x32_bf16 v[58:61], v[138:141], v[170:173], v[58:61]
	v_mfma_f32_16x16x32_bf16 v[102:105], v[130:133], v[178:181], v[102:105]
	v_mfma_f32_16x16x32_bf16 v[98:101], v[138:141], v[178:181], v[98:101]
	v_mfma_f32_16x16x32_bf16 v[94:97], v[130:133], v[186:189], v[94:97]
	v_mfma_f32_16x16x32_bf16 v[90:93], v[138:141], v[186:189], v[90:93]
	v_mfma_f32_16x16x32_bf16 v[38:41], v[134:137], v[166:169], v[38:41]
	v_mfma_f32_16x16x32_bf16 v[62:65], v[142:145], v[166:169], v[62:65]
	v_mfma_f32_16x16x32_bf16 v[34:37], v[134:137], v[174:177], v[34:37]
	v_mfma_f32_16x16x32_bf16 v[58:61], v[142:145], v[174:177], v[58:61]
	v_mfma_f32_16x16x32_bf16 v[102:105], v[134:137], v[182:185], v[102:105]
	v_mfma_f32_16x16x32_bf16 v[98:101], v[142:145], v[182:185], v[98:101]
	v_mfma_f32_16x16x32_bf16 v[94:97], v[134:137], v[190:193], v[94:97]
	v_mfma_f32_16x16x32_bf16 v[90:93], v[142:145], v[190:193], v[90:93]
	v_mfma_f32_16x16x32_bf16 v[22:25], v[146:149], v[162:165], v[22:25]
	v_mfma_f32_16x16x32_bf16 v[6:9], v[154:157], v[162:165], v[6:9]
	v_mfma_f32_16x16x32_bf16 v[18:21], v[146:149], v[170:173], v[18:21]
	v_mfma_f32_16x16x32_bf16 v[2:5], v[154:157], v[170:173], v[2:5]
	v_mfma_f32_16x16x32_bf16 v[86:89], v[146:149], v[178:181], v[86:89]
	v_mfma_f32_16x16x32_bf16 v[82:85], v[154:157], v[178:181], v[82:85]
	v_mfma_f32_16x16x32_bf16 v[78:81], v[146:149], v[186:189], v[78:81]
	v_mfma_f32_16x16x32_bf16 v[74:77], v[154:157], v[186:189], v[74:77]
	v_mfma_f32_16x16x32_bf16 v[22:25], v[150:153], v[166:169], v[22:25]
	v_mfma_f32_16x16x32_bf16 v[6:9], v[158:161], v[166:169], v[6:9]
	v_mfma_f32_16x16x32_bf16 v[18:21], v[150:153], v[174:177], v[18:21]
	v_mfma_f32_16x16x32_bf16 v[2:5], v[158:161], v[174:177], v[2:5]
	v_mfma_f32_16x16x32_bf16 v[86:89], v[150:153], v[182:185], v[86:89]
	v_mfma_f32_16x16x32_bf16 v[82:85], v[158:161], v[182:185], v[82:85]
	v_mfma_f32_16x16x32_bf16 v[78:81], v[150:153], v[190:193], v[78:81]
	s_barrier
	v_mfma_f32_16x16x32_bf16 v[74:77], v[158:161], v[190:193], v[74:77]
	s_setprio 0
	s_add_i32 s6, 0, 0x18000
	s_add_i32 s7, 0, 0x1c000
	v_add_u32_e32 v142, s6, v251
	v_add_u32_e32 v158, s7, v251
	ds_read_b128 v[130:133], v142
	ds_read_b128 v[134:137], v142 offset:1024
	ds_read_b128 v[138:141], v142 offset:2048
	ds_read_b128 v[142:145], v142 offset:3072
	ds_read_b128 v[146:149], v158
	ds_read_b128 v[150:153], v158 offset:1024
	ds_read_b128 v[154:157], v158 offset:2048
	ds_read_b128 v[158:161], v158 offset:3072
	s_add_u32 s4, s68, 0x2000
	s_addc_u32 s5, s69, 0
	s_mov_b32 m0, s77
	v_lshl_add_u64 v[202:203], s[4:5], 0, v[226:227]
	ds_read_b128 v[162:165], v244 offset:32768
	ds_read_b128 v[166:169], v244 offset:33792
	ds_read_b128 v[170:173], v244 offset:34816
	ds_read_b128 v[174:177], v244 offset:35840
	ds_read_b128 v[178:181], v244 offset:36864
	ds_read_b128 v[182:185], v244 offset:37888
	ds_read_b128 v[186:189], v244 offset:38912
	ds_read_b128 v[190:193], v244 offset:39936
	global_load_lds_dwordx4 v[202:203], off
	v_lshl_add_u64 v[202:203], s[4:5], 0, v[222:223]
	s_mov_b32 m0, s78
	s_nop 0
	global_load_lds_dwordx4 v[202:203], off
	s_waitcnt vmcnt(8)
	s_waitcnt lgkmcnt(0)
	s_barrier
	s_setprio 1
	s_waitcnt lgkmcnt(0)
	v_mfma_f32_16x16x32_bf16 v[114:117], v[130:133], v[162:165], v[114:117]
	v_mfma_f32_16x16x32_bf16 v[122:125], v[138:141], v[162:165], v[122:125]
	v_mfma_f32_16x16x32_bf16 v[118:121], v[130:133], v[170:173], v[118:121]
	v_mfma_f32_16x16x32_bf16 v[126:129], v[138:141], v[170:173], v[126:129]
	v_mfma_f32_16x16x32_bf16 v[54:57], v[130:133], v[178:181], v[54:57]
	v_mfma_f32_16x16x32_bf16 v[70:73], v[138:141], v[178:181], v[70:73]
	v_mfma_f32_16x16x32_bf16 v[50:53], v[130:133], v[186:189], v[50:53]
	v_mfma_f32_16x16x32_bf16 v[66:69], v[138:141], v[186:189], v[66:69]
	v_mfma_f32_16x16x32_bf16 v[114:117], v[134:137], v[166:169], v[114:117]
	v_mfma_f32_16x16x32_bf16 v[122:125], v[142:145], v[166:169], v[122:125]
	v_mfma_f32_16x16x32_bf16 v[118:121], v[134:137], v[174:177], v[118:121]
	v_mfma_f32_16x16x32_bf16 v[126:129], v[142:145], v[174:177], v[126:129]
	v_mfma_f32_16x16x32_bf16 v[54:57], v[134:137], v[182:185], v[54:57]
	v_mfma_f32_16x16x32_bf16 v[70:73], v[142:145], v[182:185], v[70:73]
	v_mfma_f32_16x16x32_bf16 v[50:53], v[134:137], v[190:193], v[50:53]
	v_mfma_f32_16x16x32_bf16 v[66:69], v[142:145], v[190:193], v[66:69]
	v_mfma_f32_16x16x32_bf16 v[106:109], v[146:149], v[162:165], v[106:109]
	v_mfma_f32_16x16x32_bf16 v[42:45], v[154:157], v[162:165], v[42:45]
	v_mfma_f32_16x16x32_bf16 v[110:113], v[146:149], v[170:173], v[110:113]
	v_mfma_f32_16x16x32_bf16 v[46:49], v[154:157], v[170:173], v[46:49]
	v_mfma_f32_16x16x32_bf16 v[30:33], v[146:149], v[178:181], v[30:33]
	v_mfma_f32_16x16x32_bf16 v[14:17], v[154:157], v[178:181], v[14:17]
	v_mfma_f32_16x16x32_bf16 v[26:29], v[146:149], v[186:189], v[26:29]
	v_mfma_f32_16x16x32_bf16 v[10:13], v[154:157], v[186:189], v[10:13]
	v_mfma_f32_16x16x32_bf16 v[106:109], v[150:153], v[166:169], v[106:109]
	v_mfma_f32_16x16x32_bf16 v[42:45], v[158:161], v[166:169], v[42:45]
	v_mfma_f32_16x16x32_bf16 v[110:113], v[150:153], v[174:177], v[110:113]
	v_mfma_f32_16x16x32_bf16 v[46:49], v[158:161], v[174:177], v[46:49]
	v_mfma_f32_16x16x32_bf16 v[30:33], v[150:153], v[182:185], v[30:33]
	v_mfma_f32_16x16x32_bf16 v[14:17], v[158:161], v[182:185], v[14:17]
	v_mfma_f32_16x16x32_bf16 v[26:29], v[150:153], v[190:193], v[26:29]
	s_barrier
	v_mfma_f32_16x16x32_bf16 v[10:13], v[158:161], v[190:193], v[10:13]
	s_setprio 0
	s_add_i32 s4, s6, s74
	v_lshl_add_u64 v[194:195], v[194:195], 0, s[82:83]
	s_mov_b32 m0, s4
	ds_read_b128 v[162:165], v244 offset:49152
	ds_read_b128 v[166:169], v244 offset:50176
	ds_read_b128 v[170:173], v244 offset:51200
	ds_read_b128 v[174:177], v244 offset:52224
	ds_read_b128 v[178:181], v244 offset:53248
	ds_read_b128 v[182:185], v244 offset:54272
	ds_read_b128 v[186:189], v244 offset:55296
	ds_read_b128 v[190:193], v244 offset:56320
	global_load_lds_dwordx4 v[194:195], off
	s_add_i32 m0, s4, 0x2000
	s_add_u32 s4, s66, 0x40080
	v_lshl_add_u64 v[194:195], v[196:197], 0, s[82:83]
	s_addc_u32 s5, s67, 0
	s_add_i32 s6, s7, s74
	global_load_lds_dwordx4 v[194:195], off
	v_lshl_add_u64 v[194:195], s[4:5], 0, v[0:1]
	s_mov_b32 m0, s6
	s_nop 0
	global_load_lds_dwordx4 v[194:195], off
	v_lshl_add_u64 v[194:195], s[4:5], 0, v[224:225]
	s_add_i32 m0, s6, 0x2000
	s_nop 0
	global_load_lds_dwordx4 v[194:195], off
	v_lshl_add_u64 v[194:195], v[198:199], 0, s[82:83]
	s_mov_b32 m0, s94
	s_nop 0
	global_load_lds_dwordx4 v[194:195], off
	v_lshl_add_u64 v[194:195], v[200:201], 0, s[82:83]
	s_mov_b32 m0, s95
	s_nop 0
	global_load_lds_dwordx4 v[194:195], off
	s_waitcnt vmcnt(8)
	s_waitcnt lgkmcnt(0)
	s_barrier
	s_setprio 1
	s_waitcnt lgkmcnt(0)
	v_mfma_f32_16x16x32_bf16 v[38:41], v[130:133], v[162:165], v[38:41]
	v_mfma_f32_16x16x32_bf16 v[62:65], v[138:141], v[162:165], v[62:65]
	v_mfma_f32_16x16x32_bf16 v[34:37], v[130:133], v[170:173], v[34:37]
	v_mfma_f32_16x16x32_bf16 v[58:61], v[138:141], v[170:173], v[58:61]
	v_mfma_f32_16x16x32_bf16 v[102:105], v[130:133], v[178:181], v[102:105]
	v_mfma_f32_16x16x32_bf16 v[98:101], v[138:141], v[178:181], v[98:101]
	v_mfma_f32_16x16x32_bf16 v[94:97], v[130:133], v[186:189], v[94:97]
	v_mfma_f32_16x16x32_bf16 v[90:93], v[138:141], v[186:189], v[90:93]
	v_mfma_f32_16x16x32_bf16 v[38:41], v[134:137], v[166:169], v[38:41]
	v_mfma_f32_16x16x32_bf16 v[62:65], v[142:145], v[166:169], v[62:65]
	v_mfma_f32_16x16x32_bf16 v[34:37], v[134:137], v[174:177], v[34:37]
	v_mfma_f32_16x16x32_bf16 v[58:61], v[142:145], v[174:177], v[58:61]
	v_mfma_f32_16x16x32_bf16 v[102:105], v[134:137], v[182:185], v[102:105]
	v_mfma_f32_16x16x32_bf16 v[98:101], v[142:145], v[182:185], v[98:101]
	v_mfma_f32_16x16x32_bf16 v[94:97], v[134:137], v[190:193], v[94:97]
	v_mfma_f32_16x16x32_bf16 v[90:93], v[142:145], v[190:193], v[90:93]
	v_mfma_f32_16x16x32_bf16 v[22:25], v[146:149], v[162:165], v[22:25]
	v_mfma_f32_16x16x32_bf16 v[6:9], v[154:157], v[162:165], v[6:9]
	v_mfma_f32_16x16x32_bf16 v[18:21], v[146:149], v[170:173], v[18:21]
	v_mfma_f32_16x16x32_bf16 v[2:5], v[154:157], v[170:173], v[2:5]
	v_mfma_f32_16x16x32_bf16 v[86:89], v[146:149], v[178:181], v[86:89]
	v_mfma_f32_16x16x32_bf16 v[82:85], v[154:157], v[178:181], v[82:85]
	v_mfma_f32_16x16x32_bf16 v[78:81], v[146:149], v[186:189], v[78:81]
	v_mfma_f32_16x16x32_bf16 v[74:77], v[154:157], v[186:189], v[74:77]
	v_mfma_f32_16x16x32_bf16 v[22:25], v[150:153], v[166:169], v[22:25]
	v_mfma_f32_16x16x32_bf16 v[6:9], v[158:161], v[166:169], v[6:9]
	v_mfma_f32_16x16x32_bf16 v[18:21], v[150:153], v[174:177], v[18:21]
	v_mfma_f32_16x16x32_bf16 v[2:5], v[158:161], v[174:177], v[2:5]
	v_mfma_f32_16x16x32_bf16 v[86:89], v[150:153], v[182:185], v[86:89]
	v_mfma_f32_16x16x32_bf16 v[82:85], v[158:161], v[182:185], v[82:85]
	v_mfma_f32_16x16x32_bf16 v[78:81], v[150:153], v[190:193], v[78:81]
	s_barrier
	v_mfma_f32_16x16x32_bf16 v[74:77], v[158:161], v[190:193], v[74:77]
	s_setprio 0
	s_add_i32 s73, s73, 2
	s_add_u32 s59, s59, 0x100
	s_addc_u32 s72, s72, 0
	s_cmp_gt_u32 s73, 13
	s_mov_b64 s[42:43], s[38:39]
	s_cbranch_scc0 .LBB0_390
	s_and_b64 vcc, exec, s[50:51]
	s_cbranch_vccz .LBB0_393
	s_barrier

.LBB0_451:
	s_add_u32 s30, s30, 0x80
	s_addc_u32 s31, s31, 0
	s_add_u32 s42, s34, 0x100
	v_mov_b32_e32 v2, 0
	s_addc_u32 s43, s35, 0
	s_mov_b32 s34, 0
	s_waitcnt lgkmcnt(0)
	s_add_i32 s59, s34, 2
	s_add_u32 s4, s30, 0x80
	s_addc_u32 s5, s31, 0
	s_add_i32 s6, 0, 0x10000
	s_cmp_eq_u32 s53, s34
	s_cselect_b32 s35, s27, s5
	s_cselect_b32 s34, s26, s4
	s_cselect_b32 s5, s29, s43
	s_cselect_b32 s4, s28, s42
	s_add_i32 s7, 0, 0x14000
	v_add_u32_e32 v142, s6, v184
	v_add_u32_e32 v168, s7, v184
	ds_read_b128 v[130:133], v142
	ds_read_b128 v[134:137], v142 offset:1024
	ds_read_b128 v[138:141], v142 offset:2048
	ds_read_b128 v[142:145], v142 offset:3072
	ds_read_b128 v[146:149], v168
	ds_read_b128 v[150:153], v168 offset:1024
	ds_read_b128 v[154:157], v168 offset:2048
	ds_read_b128 v[168:171], v168 offset:3072
	v_lshl_add_u64 v[180:181], s[30:31], 0, v[164:165]
	s_add_i32 m0, s38, 0xc000
	ds_read_b128 v[172:175], v187
	ds_read_b128 v[176:179], v187 offset:1024
	ds_read_b128 v[188:191], v187 offset:2048
	ds_read_b128 v[192:195], v187 offset:3072
	ds_read_b128 v[196:199], v187 offset:4096
	ds_read_b128 v[200:203], v187 offset:5120
	ds_read_b128 v[204:207], v187 offset:6144
	ds_read_b128 v[222:225], v187 offset:7168
	global_load_lds_dwordx4 v[180:181], off
	v_lshl_add_u64 v[180:181], s[30:31], 0, v[166:167]
	s_add_i32 m0, s38, 0xe000
	s_nop 0
	global_load_lds_dwordx4 v[180:181], off
	s_waitcnt vmcnt(8)
	s_waitcnt lgkmcnt(0)
	s_barrier
	s_setprio 1
	s_waitcnt lgkmcnt(0)
	v_mfma_f32_16x16x32_bf16 v[126:129], v[130:133], v[172:175], 0
	v_mfma_f32_16x16x32_bf16 v[122:125], v[138:141], v[172:175], 0
	v_mfma_f32_16x16x32_bf16 v[110:113], v[130:133], v[188:191], 0
	v_mfma_f32_16x16x32_bf16 v[106:109], v[138:141], v[188:191], 0
	v_mfma_f32_16x16x32_bf16 v[98:101], v[130:133], v[196:199], 0
	v_mfma_f32_16x16x32_bf16 v[90:93], v[138:141], v[196:199], 0
	v_mfma_f32_16x16x32_bf16 v[82:85], v[130:133], v[204:207], 0
	v_mfma_f32_16x16x32_bf16 v[74:77], v[138:141], v[204:207], 0
	v_mfma_f32_16x16x32_bf16 v[126:129], v[134:137], v[176:179], v[126:129]
	v_mfma_f32_16x16x32_bf16 v[122:125], v[142:145], v[176:179], v[122:125]
	v_mfma_f32_16x16x32_bf16 v[110:113], v[134:137], v[192:195], v[110:113]
	v_mfma_f32_16x16x32_bf16 v[106:109], v[142:145], v[192:195], v[106:109]
	v_mfma_f32_16x16x32_bf16 v[98:101], v[134:137], v[200:203], v[98:101]
	v_mfma_f32_16x16x32_bf16 v[90:93], v[142:145], v[200:203], v[90:93]
	v_mfma_f32_16x16x32_bf16 v[82:85], v[134:137], v[222:225], v[82:85]
	v_mfma_f32_16x16x32_bf16 v[74:77], v[142:145], v[222:225], v[74:77]
	v_mfma_f32_16x16x32_bf16 v[118:121], v[146:149], v[172:175], 0
	v_mfma_f32_16x16x32_bf16 v[114:117], v[154:157], v[172:175], 0
	v_mfma_f32_16x16x32_bf16 v[102:105], v[146:149], v[188:191], 0
	v_mfma_f32_16x16x32_bf16 v[94:97], v[154:157], v[188:191], 0
	v_mfma_f32_16x16x32_bf16 v[86:89], v[146:149], v[196:199], 0
	v_mfma_f32_16x16x32_bf16 v[78:81], v[154:157], v[196:199], 0
	v_mfma_f32_16x16x32_bf16 v[70:73], v[146:149], v[204:207], 0
	v_mfma_f32_16x16x32_bf16 v[66:69], v[154:157], v[204:207], 0
	v_mfma_f32_16x16x32_bf16 v[118:121], v[150:153], v[176:179], v[118:121]
	v_mfma_f32_16x16x32_bf16 v[114:117], v[168:171], v[176:179], v[114:117]
	v_mfma_f32_16x16x32_bf16 v[102:105], v[150:153], v[192:195], v[102:105]
	v_mfma_f32_16x16x32_bf16 v[94:97], v[168:171], v[192:195], v[94:97]
	v_mfma_f32_16x16x32_bf16 v[86:89], v[150:153], v[200:203], v[86:89]
	v_mfma_f32_16x16x32_bf16 v[78:81], v[168:171], v[200:203], v[78:81]
	v_mfma_f32_16x16x32_bf16 v[70:73], v[150:153], v[222:225], v[70:73]
	s_barrier
	v_mfma_f32_16x16x32_bf16 v[66:69], v[168:171], v[222:225], v[66:69]
	s_setprio 0
	s_add_i32 s6, s6, s37
	v_lshl_add_u64 v[180:181], s[4:5], 0, v[0:1]
	s_mov_b32 m0, s6
	ds_read_b128 v[172:175], v187 offset:16384
	ds_read_b128 v[176:179], v187 offset:17408
	ds_read_b128 v[188:191], v187 offset:18432
	ds_read_b128 v[192:195], v187 offset:19456
	ds_read_b128 v[196:199], v187 offset:20480
	ds_read_b128 v[200:203], v187 offset:21504
	ds_read_b128 v[204:207], v187 offset:22528
	ds_read_b128 v[222:225], v187 offset:23552
	global_load_lds_dwordx4 v[180:181], off
	s_add_i32 m0, s6, 0x2000
	v_lshl_add_u64 v[208:209], s[4:5], 0, v[160:161]
	s_add_u32 s4, s4, s84
	s_addc_u32 s5, s5, 0
	s_add_i32 s6, s7, s37
	global_load_lds_dwordx4 v[208:209], off
	v_lshl_add_u64 v[226:227], s[4:5], 0, v[0:1]
	s_mov_b32 m0, s6
	v_lshl_add_u64 v[228:229], s[4:5], 0, v[160:161]
	global_load_lds_dwordx4 v[226:227], off
	s_add_i32 m0, s6, 0x2000
	v_lshl_add_u64 v[230:231], s[34:35], 0, v[162:163]
	global_load_lds_dwordx4 v[228:229], off
	s_mov_b32 m0, s38
	v_lshl_add_u64 v[232:233], s[34:35], 0, v[158:159]
	global_load_lds_dwordx4 v[230:231], off
	s_mov_b32 m0, s39
	s_nop 0
	global_load_lds_dwordx4 v[232:233], off
	s_waitcnt vmcnt(8)
	s_waitcnt lgkmcnt(0)
	s_barrier
	s_setprio 1
	s_waitcnt lgkmcnt(0)
	v_mfma_f32_16x16x32_bf16 v[62:65], v[130:133], v[172:175], 0
	v_mfma_f32_16x16x32_bf16 v[58:61], v[138:141], v[172:175], 0
	v_mfma_f32_16x16x32_bf16 v[46:49], v[130:133], v[188:191], 0
	v_mfma_f32_16x16x32_bf16 v[42:45], v[138:141], v[188:191], 0
	v_mfma_f32_16x16x32_bf16 v[34:37], v[130:133], v[196:199], 0
	v_mfma_f32_16x16x32_bf16 v[26:29], v[138:141], v[196:199], 0
	v_mfma_f32_16x16x32_bf16 v[18:21], v[130:133], v[204:207], 0
	v_mfma_f32_16x16x32_bf16 v[10:13], v[138:141], v[204:207], 0
	v_mfma_f32_16x16x32_bf16 v[62:65], v[134:137], v[176:179], v[62:65]
	v_mfma_f32_16x16x32_bf16 v[58:61], v[142:145], v[176:179], v[58:61]
	v_mfma_f32_16x16x32_bf16 v[46:49], v[134:137], v[192:195], v[46:49]
	v_mfma_f32_16x16x32_bf16 v[42:45], v[142:145], v[192:195], v[42:45]
	v_mfma_f32_16x16x32_bf16 v[34:37], v[134:137], v[200:203], v[34:37]
	v_mfma_f32_16x16x32_bf16 v[26:29], v[142:145], v[200:203], v[26:29]
	v_mfma_f32_16x16x32_bf16 v[18:21], v[134:137], v[222:225], v[18:21]
	v_mfma_f32_16x16x32_bf16 v[10:13], v[142:145], v[222:225], v[10:13]
	v_mfma_f32_16x16x32_bf16 v[54:57], v[146:149], v[172:175], 0
	v_mfma_f32_16x16x32_bf16 v[50:53], v[154:157], v[172:175], 0
	v_mfma_f32_16x16x32_bf16 v[38:41], v[146:149], v[188:191], 0
	v_mfma_f32_16x16x32_bf16 v[30:33], v[154:157], v[188:191], 0
	v_mfma_f32_16x16x32_bf16 v[22:25], v[146:149], v[196:199], 0
	v_mfma_f32_16x16x32_bf16 v[14:17], v[154:157], v[196:199], 0
	v_mfma_f32_16x16x32_bf16 v[6:9], v[146:149], v[204:207], 0
	v_mfma_f32_16x16x32_bf16 v[2:5], v[154:157], v[204:207], 0
	v_mfma_f32_16x16x32_bf16 v[54:57], v[150:153], v[176:179], v[54:57]
	v_mfma_f32_16x16x32_bf16 v[50:53], v[168:171], v[176:179], v[50:53]
	v_mfma_f32_16x16x32_bf16 v[38:41], v[150:153], v[192:195], v[38:41]
	v_mfma_f32_16x16x32_bf16 v[30:33], v[168:171], v[192:195], v[30:33]
	v_mfma_f32_16x16x32_bf16 v[22:25], v[150:153], v[200:203], v[22:25]
	v_mfma_f32_16x16x32_bf16 v[14:17], v[168:171], v[200:203], v[14:17]
	v_mfma_f32_16x16x32_bf16 v[6:9], v[150:153], v[222:225], v[6:9]
	s_barrier
	v_mfma_f32_16x16x32_bf16 v[2:5], v[168:171], v[222:225], v[2:5]
	s_setprio 0
	s_add_i32 s6, 0, 0x18000
	s_add_i32 s7, 0, 0x1c000
	v_add_u32_e32 v142, s6, v184
	v_add_u32_e32 v168, s7, v184
	ds_read_b128 v[130:133], v142
	ds_read_b128 v[134:137], v142 offset:1024
	ds_read_b128 v[138:141], v142 offset:2048
	ds_read_b128 v[142:145], v142 offset:3072
	ds_read_b128 v[146:149], v168
	ds_read_b128 v[150:153], v168 offset:1024
	ds_read_b128 v[154:157], v168 offset:2048
	ds_read_b128 v[168:171], v168 offset:3072
	s_add_u32 s4, s34, s84
	s_addc_u32 s5, s35, 0
	s_mov_b32 m0, s45
	v_lshl_add_u64 v[234:235], s[4:5], 0, v[162:163]
	ds_read_b128 v[172:175], v187 offset:32768
	ds_read_b128 v[176:179], v187 offset:33792
	ds_read_b128 v[188:191], v187 offset:34816
	ds_read_b128 v[192:195], v187 offset:35840
	ds_read_b128 v[196:199], v187 offset:36864
	ds_read_b128 v[200:203], v187 offset:37888
	ds_read_b128 v[204:207], v187 offset:38912
	ds_read_b128 v[222:225], v187 offset:39936
	global_load_lds_dwordx4 v[234:235], off
	v_lshl_add_u64 v[234:235], s[4:5], 0, v[158:159]
	s_mov_b32 m0, s46
	s_nop 0
	global_load_lds_dwordx4 v[234:235], off
	s_waitcnt vmcnt(8)
	s_waitcnt lgkmcnt(0)
	s_barrier
	s_setprio 1
	s_waitcnt lgkmcnt(0)
	v_mfma_f32_16x16x32_bf16 v[126:129], v[130:133], v[172:175], v[126:129]
	v_mfma_f32_16x16x32_bf16 v[122:125], v[138:141], v[172:175], v[122:125]
	v_mfma_f32_16x16x32_bf16 v[110:113], v[130:133], v[188:191], v[110:113]
	v_mfma_f32_16x16x32_bf16 v[106:109], v[138:141], v[188:191], v[106:109]
	v_mfma_f32_16x16x32_bf16 v[98:101], v[130:133], v[196:199], v[98:101]
	v_mfma_f32_16x16x32_bf16 v[90:93], v[138:141], v[196:199], v[90:93]
	v_mfma_f32_16x16x32_bf16 v[82:85], v[130:133], v[204:207], v[82:85]
	v_mfma_f32_16x16x32_bf16 v[74:77], v[138:141], v[204:207], v[74:77]
	v_mfma_f32_16x16x32_bf16 v[126:129], v[134:137], v[176:179], v[126:129]
	v_mfma_f32_16x16x32_bf16 v[122:125], v[142:145], v[176:179], v[122:125]
	v_mfma_f32_16x16x32_bf16 v[110:113], v[134:137], v[192:195], v[110:113]
	v_mfma_f32_16x16x32_bf16 v[106:109], v[142:145], v[192:195], v[106:109]
	v_mfma_f32_16x16x32_bf16 v[98:101], v[134:137], v[200:203], v[98:101]
	v_mfma_f32_16x16x32_bf16 v[90:93], v[142:145], v[200:203], v[90:93]
	v_mfma_f32_16x16x32_bf16 v[82:85], v[134:137], v[222:225], v[82:85]
	v_mfma_f32_16x16x32_bf16 v[74:77], v[142:145], v[222:225], v[74:77]
	v_mfma_f32_16x16x32_bf16 v[118:121], v[146:149], v[172:175], v[118:121]
	v_mfma_f32_16x16x32_bf16 v[114:117], v[154:157], v[172:175], v[114:117]
	v_mfma_f32_16x16x32_bf16 v[102:105], v[146:149], v[188:191], v[102:105]
	v_mfma_f32_16x16x32_bf16 v[94:97], v[154:157], v[188:191], v[94:97]
	v_mfma_f32_16x16x32_bf16 v[86:89], v[146:149], v[196:199], v[86:89]
	v_mfma_f32_16x16x32_bf16 v[78:81], v[154:157], v[196:199], v[78:81]
	v_mfma_f32_16x16x32_bf16 v[70:73], v[146:149], v[204:207], v[70:73]
	v_mfma_f32_16x16x32_bf16 v[66:69], v[154:157], v[204:207], v[66:69]
	v_mfma_f32_16x16x32_bf16 v[118:121], v[150:153], v[176:179], v[118:121]
	v_mfma_f32_16x16x32_bf16 v[114:117], v[168:171], v[176:179], v[114:117]
	v_mfma_f32_16x16x32_bf16 v[102:105], v[150:153], v[192:195], v[102:105]
	v_mfma_f32_16x16x32_bf16 v[94:97], v[168:171], v[192:195], v[94:97]
	v_mfma_f32_16x16x32_bf16 v[86:89], v[150:153], v[200:203], v[86:89]
	v_mfma_f32_16x16x32_bf16 v[78:81], v[168:171], v[200:203], v[78:81]
	v_mfma_f32_16x16x32_bf16 v[70:73], v[150:153], v[222:225], v[70:73]
	s_barrier
	v_mfma_f32_16x16x32_bf16 v[66:69], v[168:171], v[222:225], v[66:69]
	s_setprio 0
	s_add_i32 s4, s6, s37
	v_lshl_add_u64 v[180:181], v[180:181], 0, s[82:83]
	s_mov_b32 m0, s4
	ds_read_b128 v[172:175], v187 offset:49152
	ds_read_b128 v[176:179], v187 offset:50176
	ds_read_b128 v[188:191], v187 offset:51200
	ds_read_b128 v[192:195], v187 offset:52224
	ds_read_b128 v[196:199], v187 offset:53248
	ds_read_b128 v[200:203], v187 offset:54272
	ds_read_b128 v[204:207], v187 offset:55296
	ds_read_b128 v[222:225], v187 offset:56320
	global_load_lds_dwordx4 v[180:181], off
	v_lshl_add_u64 v[180:181], v[208:209], 0, s[82:83]
	s_add_i32 m0, s4, 0x2000
	s_add_i32 s4, s7, s37
	global_load_lds_dwordx4 v[180:181], off
	v_lshl_add_u64 v[180:181], v[226:227], 0, s[82:83]
	s_mov_b32 m0, s4
	s_nop 0
	global_load_lds_dwordx4 v[180:181], off
	v_lshl_add_u64 v[180:181], v[228:229], 0, s[82:83]
	s_add_i32 m0, s4, 0x2000
	s_nop 0
	global_load_lds_dwordx4 v[180:181], off
	v_lshl_add_u64 v[180:181], v[230:231], 0, s[82:83]
	s_mov_b32 m0, s51
	s_nop 0
	global_load_lds_dwordx4 v[180:181], off
	v_lshl_add_u64 v[180:181], v[232:233], 0, s[82:83]
	s_mov_b32 m0, s52
	s_nop 0
	global_load_lds_dwordx4 v[180:181], off
	s_waitcnt vmcnt(8)
	s_waitcnt lgkmcnt(0)
	s_barrier
	s_setprio 1
	s_waitcnt lgkmcnt(0)
	v_mfma_f32_16x16x32_bf16 v[62:65], v[130:133], v[172:175], v[62:65]
	v_mfma_f32_16x16x32_bf16 v[58:61], v[138:141], v[172:175], v[58:61]
	v_mfma_f32_16x16x32_bf16 v[46:49], v[130:133], v[188:191], v[46:49]
	v_mfma_f32_16x16x32_bf16 v[42:45], v[138:141], v[188:191], v[42:45]
	v_mfma_f32_16x16x32_bf16 v[34:37], v[130:133], v[196:199], v[34:37]
	v_mfma_f32_16x16x32_bf16 v[26:29], v[138:141], v[196:199], v[26:29]
	v_mfma_f32_16x16x32_bf16 v[18:21], v[130:133], v[204:207], v[18:21]
	v_mfma_f32_16x16x32_bf16 v[10:13], v[138:141], v[204:207], v[10:13]
	v_mfma_f32_16x16x32_bf16 v[62:65], v[134:137], v[176:179], v[62:65]
	v_mfma_f32_16x16x32_bf16 v[58:61], v[142:145], v[176:179], v[58:61]
	v_mfma_f32_16x16x32_bf16 v[46:49], v[134:137], v[192:195], v[46:49]
	v_mfma_f32_16x16x32_bf16 v[42:45], v[142:145], v[192:195], v[42:45]
	v_mfma_f32_16x16x32_bf16 v[34:37], v[134:137], v[200:203], v[34:37]
	v_mfma_f32_16x16x32_bf16 v[26:29], v[142:145], v[200:203], v[26:29]
	v_mfma_f32_16x16x32_bf16 v[18:21], v[134:137], v[222:225], v[18:21]
	v_mfma_f32_16x16x32_bf16 v[10:13], v[142:145], v[222:225], v[10:13]
	v_mfma_f32_16x16x32_bf16 v[54:57], v[146:149], v[172:175], v[54:57]
	v_mfma_f32_16x16x32_bf16 v[50:53], v[154:157], v[172:175], v[50:53]
	v_mfma_f32_16x16x32_bf16 v[38:41], v[146:149], v[188:191], v[38:41]
	v_mfma_f32_16x16x32_bf16 v[30:33], v[154:157], v[188:191], v[30:33]
	v_mfma_f32_16x16x32_bf16 v[22:25], v[146:149], v[196:199], v[22:25]
	v_mfma_f32_16x16x32_bf16 v[14:17], v[154:157], v[196:199], v[14:17]
	v_mfma_f32_16x16x32_bf16 v[6:9], v[146:149], v[204:207], v[6:9]
	v_mfma_f32_16x16x32_bf16 v[2:5], v[154:157], v[204:207], v[2:5]
	v_mfma_f32_16x16x32_bf16 v[54:57], v[150:153], v[176:179], v[54:57]
	v_mfma_f32_16x16x32_bf16 v[50:53], v[168:171], v[176:179], v[50:53]
	v_mfma_f32_16x16x32_bf16 v[38:41], v[150:153], v[192:195], v[38:41]
	v_mfma_f32_16x16x32_bf16 v[30:33], v[168:171], v[192:195], v[30:33]
	v_mfma_f32_16x16x32_bf16 v[22:25], v[150:153], v[200:203], v[22:25]
	v_mfma_f32_16x16x32_bf16 v[14:17], v[168:171], v[200:203], v[14:17]
	v_mfma_f32_16x16x32_bf16 v[6:9], v[150:153], v[222:225], v[6:9]
	s_barrier
	v_mfma_f32_16x16x32_bf16 v[2:5], v[168:171], v[222:225], v[2:5]
	s_setprio 0
	s_add_u32 s30, s30, 0x100
	s_addc_u32 s31, s31, 0
	s_add_u32 s42, s42, 0x100
	s_addc_u32 s43, s43, 0
	s_cmp_ge_u32 s59, s48
	s_mov_b32 s34, s59
.LBB0_452:
	s_add_i32 s59, s34, 2
	s_add_u32 s4, s30, 0x80
	s_addc_u32 s5, s31, 0
	s_add_i32 s6, 0, 0x10000
	s_cmp_eq_u32 s53, s34
	s_cselect_b32 s35, s27, s5
	s_cselect_b32 s34, s26, s4
	s_cselect_b32 s5, s29, s43
	s_cselect_b32 s4, s28, s42
	s_add_i32 s7, 0, 0x14000
	v_add_u32_e32 v142, s6, v184
	v_add_u32_e32 v168, s7, v184
	ds_read_b128 v[130:133], v142
	ds_read_b128 v[134:137], v142 offset:1024
	ds_read_b128 v[138:141], v142 offset:2048
	ds_read_b128 v[142:145], v142 offset:3072
	ds_read_b128 v[146:149], v168
	ds_read_b128 v[150:153], v168 offset:1024
	ds_read_b128 v[154:157], v168 offset:2048
	ds_read_b128 v[168:171], v168 offset:3072
	v_lshl_add_u64 v[180:181], s[30:31], 0, v[164:165]
	s_add_i32 m0, s38, 0xc000
	ds_read_b128 v[172:175], v187
	ds_read_b128 v[176:179], v187 offset:1024
	ds_read_b128 v[188:191], v187 offset:2048
	ds_read_b128 v[192:195], v187 offset:3072
	ds_read_b128 v[196:199], v187 offset:4096
	ds_read_b128 v[200:203], v187 offset:5120
	ds_read_b128 v[204:207], v187 offset:6144
	ds_read_b128 v[222:225], v187 offset:7168
	global_load_lds_dwordx4 v[180:181], off
	v_lshl_add_u64 v[180:181], s[30:31], 0, v[166:167]
	s_add_i32 m0, s38, 0xe000
	s_nop 0
	global_load_lds_dwordx4 v[180:181], off
	s_waitcnt vmcnt(8)
	s_waitcnt lgkmcnt(0)
	s_barrier
	s_setprio 1
	s_waitcnt lgkmcnt(0)
	v_mfma_f32_16x16x32_bf16 v[126:129], v[130:133], v[172:175], v[126:129]
	v_mfma_f32_16x16x32_bf16 v[122:125], v[138:141], v[172:175], v[122:125]
	v_mfma_f32_16x16x32_bf16 v[110:113], v[130:133], v[188:191], v[110:113]
	v_mfma_f32_16x16x32_bf16 v[106:109], v[138:141], v[188:191], v[106:109]
	v_mfma_f32_16x16x32_bf16 v[98:101], v[130:133], v[196:199], v[98:101]
	v_mfma_f32_16x16x32_bf16 v[90:93], v[138:141], v[196:199], v[90:93]
	v_mfma_f32_16x16x32_bf16 v[82:85], v[130:133], v[204:207], v[82:85]
	v_mfma_f32_16x16x32_bf16 v[74:77], v[138:141], v[204:207], v[74:77]
	v_mfma_f32_16x16x32_bf16 v[126:129], v[134:137], v[176:179], v[126:129]
	v_mfma_f32_16x16x32_bf16 v[122:125], v[142:145], v[176:179], v[122:125]
	v_mfma_f32_16x16x32_bf16 v[110:113], v[134:137], v[192:195], v[110:113]
	v_mfma_f32_16x16x32_bf16 v[106:109], v[142:145], v[192:195], v[106:109]
	v_mfma_f32_16x16x32_bf16 v[98:101], v[134:137], v[200:203], v[98:101]
	v_mfma_f32_16x16x32_bf16 v[90:93], v[142:145], v[200:203], v[90:93]
	v_mfma_f32_16x16x32_bf16 v[82:85], v[134:137], v[222:225], v[82:85]
	v_mfma_f32_16x16x32_bf16 v[74:77], v[142:145], v[222:225], v[74:77]
	v_mfma_f32_16x16x32_bf16 v[118:121], v[146:149], v[172:175], v[118:121]
	v_mfma_f32_16x16x32_bf16 v[114:117], v[154:157], v[172:175], v[114:117]
	v_mfma_f32_16x16x32_bf16 v[102:105], v[146:149], v[188:191], v[102:105]
	v_mfma_f32_16x16x32_bf16 v[94:97], v[154:157], v[188:191], v[94:97]
	v_mfma_f32_16x16x32_bf16 v[86:89], v[146:149], v[196:199], v[86:89]
	v_mfma_f32_16x16x32_bf16 v[78:81], v[154:157], v[196:199], v[78:81]
	v_mfma_f32_16x16x32_bf16 v[70:73], v[146:149], v[204:207], v[70:73]
	v_mfma_f32_16x16x32_bf16 v[66:69], v[154:157], v[204:207], v[66:69]
	v_mfma_f32_16x16x32_bf16 v[118:121], v[150:153], v[176:179], v[118:121]
	v_mfma_f32_16x16x32_bf16 v[114:117], v[168:171], v[176:179], v[114:117]
	v_mfma_f32_16x16x32_bf16 v[102:105], v[150:153], v[192:195], v[102:105]
	v_mfma_f32_16x16x32_bf16 v[94:97], v[168:171], v[192:195], v[94:97]
	v_mfma_f32_16x16x32_bf16 v[86:89], v[150:153], v[200:203], v[86:89]
	v_mfma_f32_16x16x32_bf16 v[78:81], v[168:171], v[200:203], v[78:81]
	v_mfma_f32_16x16x32_bf16 v[70:73], v[150:153], v[222:225], v[70:73]
	s_barrier
	v_mfma_f32_16x16x32_bf16 v[66:69], v[168:171], v[222:225], v[66:69]
	s_setprio 0
	s_add_i32 s6, s6, s37
	v_lshl_add_u64 v[180:181], s[4:5], 0, v[0:1]
	s_mov_b32 m0, s6
	ds_read_b128 v[172:175], v187 offset:16384
	ds_read_b128 v[176:179], v187 offset:17408
	ds_read_b128 v[188:191], v187 offset:18432
	ds_read_b128 v[192:195], v187 offset:19456
	ds_read_b128 v[196:199], v187 offset:20480
	ds_read_b128 v[200:203], v187 offset:21504
	ds_read_b128 v[204:207], v187 offset:22528
	ds_read_b128 v[222:225], v187 offset:23552
	global_load_lds_dwordx4 v[180:181], off
	s_add_i32 m0, s6, 0x2000
	v_lshl_add_u64 v[208:209], s[4:5], 0, v[160:161]
	s_add_u32 s4, s4, s84
	s_addc_u32 s5, s5, 0
	s_add_i32 s6, s7, s37
	global_load_lds_dwordx4 v[208:209], off
	v_lshl_add_u64 v[226:227], s[4:5], 0, v[0:1]
	s_mov_b32 m0, s6
	v_lshl_add_u64 v[228:229], s[4:5], 0, v[160:161]
	global_load_lds_dwordx4 v[226:227], off
	s_add_i32 m0, s6, 0x2000
	v_lshl_add_u64 v[230:231], s[34:35], 0, v[162:163]
	global_load_lds_dwordx4 v[228:229], off
	s_mov_b32 m0, s38
	v_lshl_add_u64 v[232:233], s[34:35], 0, v[158:159]
	global_load_lds_dwordx4 v[230:231], off
	s_mov_b32 m0, s39
	s_nop 0
	global_load_lds_dwordx4 v[232:233], off
	s_waitcnt vmcnt(8)
	s_waitcnt lgkmcnt(0)
	s_barrier
	s_setprio 1
	s_waitcnt lgkmcnt(0)
	v_mfma_f32_16x16x32_bf16 v[62:65], v[130:133], v[172:175], v[62:65]
	v_mfma_f32_16x16x32_bf16 v[58:61], v[138:141], v[172:175], v[58:61]
	v_mfma_f32_16x16x32_bf16 v[46:49], v[130:133], v[188:191], v[46:49]
	v_mfma_f32_16x16x32_bf16 v[42:45], v[138:141], v[188:191], v[42:45]
	v_mfma_f32_16x16x32_bf16 v[34:37], v[130:133], v[196:199], v[34:37]
	v_mfma_f32_16x16x32_bf16 v[26:29], v[138:141], v[196:199], v[26:29]
	v_mfma_f32_16x16x32_bf16 v[18:21], v[130:133], v[204:207], v[18:21]
	v_mfma_f32_16x16x32_bf16 v[10:13], v[138:141], v[204:207], v[10:13]
	v_mfma_f32_16x16x32_bf16 v[62:65], v[134:137], v[176:179], v[62:65]
	v_mfma_f32_16x16x32_bf16 v[58:61], v[142:145], v[176:179], v[58:61]
	v_mfma_f32_16x16x32_bf16 v[46:49], v[134:137], v[192:195], v[46:49]
	v_mfma_f32_16x16x32_bf16 v[42:45], v[142:145], v[192:195], v[42:45]
	v_mfma_f32_16x16x32_bf16 v[34:37], v[134:137], v[200:203], v[34:37]
	v_mfma_f32_16x16x32_bf16 v[26:29], v[142:145], v[200:203], v[26:29]
	v_mfma_f32_16x16x32_bf16 v[18:21], v[134:137], v[222:225], v[18:21]
	v_mfma_f32_16x16x32_bf16 v[10:13], v[142:145], v[222:225], v[10:13]
	v_mfma_f32_16x16x32_bf16 v[54:57], v[146:149], v[172:175], v[54:57]
	v_mfma_f32_16x16x32_bf16 v[50:53], v[154:157], v[172:175], v[50:53]
	v_mfma_f32_16x16x32_bf16 v[38:41], v[146:149], v[188:191], v[38:41]
	v_mfma_f32_16x16x32_bf16 v[30:33], v[154:157], v[188:191], v[30:33]
	v_mfma_f32_16x16x32_bf16 v[22:25], v[146:149], v[196:199], v[22:25]
	v_mfma_f32_16x16x32_bf16 v[14:17], v[154:157], v[196:199], v[14:17]
	v_mfma_f32_16x16x32_bf16 v[6:9], v[146:149], v[204:207], v[6:9]
	v_mfma_f32_16x16x32_bf16 v[2:5], v[154:157], v[204:207], v[2:5]
	v_mfma_f32_16x16x32_bf16 v[54:57], v[150:153], v[176:179], v[54:57]
	v_mfma_f32_16x16x32_bf16 v[50:53], v[168:171], v[176:179], v[50:53]
	v_mfma_f32_16x16x32_bf16 v[38:41], v[150:153], v[192:195], v[38:41]
	v_mfma_f32_16x16x32_bf16 v[30:33], v[168:171], v[192:195], v[30:33]
	v_mfma_f32_16x16x32_bf16 v[22:25], v[150:153], v[200:203], v[22:25]
	v_mfma_f32_16x16x32_bf16 v[14:17], v[168:171], v[200:203], v[14:17]
	v_mfma_f32_16x16x32_bf16 v[6:9], v[150:153], v[222:225], v[6:9]
	s_barrier
	v_mfma_f32_16x16x32_bf16 v[2:5], v[168:171], v[222:225], v[2:5]
	s_setprio 0
	s_add_i32 s6, 0, 0x18000
	s_add_i32 s7, 0, 0x1c000
	v_add_u32_e32 v142, s6, v184
	v_add_u32_e32 v168, s7, v184
	ds_read_b128 v[130:133], v142
	ds_read_b128 v[134:137], v142 offset:1024
	ds_read_b128 v[138:141], v142 offset:2048
	ds_read_b128 v[142:145], v142 offset:3072
	ds_read_b128 v[146:149], v168
	ds_read_b128 v[150:153], v168 offset:1024
	ds_read_b128 v[154:157], v168 offset:2048
	ds_read_b128 v[168:171], v168 offset:3072
	s_add_u32 s4, s34, s84
	s_addc_u32 s5, s35, 0
	s_mov_b32 m0, s45
	v_lshl_add_u64 v[234:235], s[4:5], 0, v[162:163]
	ds_read_b128 v[172:175], v187 offset:32768
	ds_read_b128 v[176:179], v187 offset:33792
	ds_read_b128 v[188:191], v187 offset:34816
	ds_read_b128 v[192:195], v187 offset:35840
	ds_read_b128 v[196:199], v187 offset:36864
	ds_read_b128 v[200:203], v187 offset:37888
	ds_read_b128 v[204:207], v187 offset:38912
	ds_read_b128 v[222:225], v187 offset:39936
	global_load_lds_dwordx4 v[234:235], off
	v_lshl_add_u64 v[234:235], s[4:5], 0, v[158:159]
	s_mov_b32 m0, s46
	s_nop 0
	global_load_lds_dwordx4 v[234:235], off
	s_waitcnt vmcnt(8)
	s_waitcnt lgkmcnt(0)
	s_barrier
	s_setprio 1
	s_waitcnt lgkmcnt(0)
	v_mfma_f32_16x16x32_bf16 v[126:129], v[130:133], v[172:175], v[126:129]
	v_mfma_f32_16x16x32_bf16 v[122:125], v[138:141], v[172:175], v[122:125]
	v_mfma_f32_16x16x32_bf16 v[110:113], v[130:133], v[188:191], v[110:113]
	v_mfma_f32_16x16x32_bf16 v[106:109], v[138:141], v[188:191], v[106:109]
	v_mfma_f32_16x16x32_bf16 v[98:101], v[130:133], v[196:199], v[98:101]
	v_mfma_f32_16x16x32_bf16 v[90:93], v[138:141], v[196:199], v[90:93]
	v_mfma_f32_16x16x32_bf16 v[82:85], v[130:133], v[204:207], v[82:85]
	v_mfma_f32_16x16x32_bf16 v[74:77], v[138:141], v[204:207], v[74:77]
	v_mfma_f32_16x16x32_bf16 v[126:129], v[134:137], v[176:179], v[126:129]
	v_mfma_f32_16x16x32_bf16 v[122:125], v[142:145], v[176:179], v[122:125]
	v_mfma_f32_16x16x32_bf16 v[110:113], v[134:137], v[192:195], v[110:113]
	v_mfma_f32_16x16x32_bf16 v[106:109], v[142:145], v[192:195], v[106:109]
	v_mfma_f32_16x16x32_bf16 v[98:101], v[134:137], v[200:203], v[98:101]
	v_mfma_f32_16x16x32_bf16 v[90:93], v[142:145], v[200:203], v[90:93]
	v_mfma_f32_16x16x32_bf16 v[82:85], v[134:137], v[222:225], v[82:85]
	v_mfma_f32_16x16x32_bf16 v[74:77], v[142:145], v[222:225], v[74:77]
	v_mfma_f32_16x16x32_bf16 v[118:121], v[146:149], v[172:175], v[118:121]
	v_mfma_f32_16x16x32_bf16 v[114:117], v[154:157], v[172:175], v[114:117]
	v_mfma_f32_16x16x32_bf16 v[102:105], v[146:149], v[188:191], v[102:105]
	v_mfma_f32_16x16x32_bf16 v[94:97], v[154:157], v[188:191], v[94:97]
	v_mfma_f32_16x16x32_bf16 v[86:89], v[146:149], v[196:199], v[86:89]
	v_mfma_f32_16x16x32_bf16 v[78:81], v[154:157], v[196:199], v[78:81]
	v_mfma_f32_16x16x32_bf16 v[70:73], v[146:149], v[204:207], v[70:73]
	v_mfma_f32_16x16x32_bf16 v[66:69], v[154:157], v[204:207], v[66:69]
	v_mfma_f32_16x16x32_bf16 v[118:121], v[150:153], v[176:179], v[118:121]
	v_mfma_f32_16x16x32_bf16 v[114:117], v[168:171], v[176:179], v[114:117]
	v_mfma_f32_16x16x32_bf16 v[102:105], v[150:153], v[192:195], v[102:105]
	v_mfma_f32_16x16x32_bf16 v[94:97], v[168:171], v[192:195], v[94:97]
	v_mfma_f32_16x16x32_bf16 v[86:89], v[150:153], v[200:203], v[86:89]
	v_mfma_f32_16x16x32_bf16 v[78:81], v[168:171], v[200:203], v[78:81]
	v_mfma_f32_16x16x32_bf16 v[70:73], v[150:153], v[222:225], v[70:73]
	s_barrier
	v_mfma_f32_16x16x32_bf16 v[66:69], v[168:171], v[222:225], v[66:69]
	s_setprio 0
	s_add_i32 s4, s6, s37
	v_lshl_add_u64 v[180:181], v[180:181], 0, s[82:83]
	s_mov_b32 m0, s4
	ds_read_b128 v[172:175], v187 offset:49152
	ds_read_b128 v[176:179], v187 offset:50176
	ds_read_b128 v[188:191], v187 offset:51200
	ds_read_b128 v[192:195], v187 offset:52224
	ds_read_b128 v[196:199], v187 offset:53248
	ds_read_b128 v[200:203], v187 offset:54272
	ds_read_b128 v[204:207], v187 offset:55296
	ds_read_b128 v[222:225], v187 offset:56320
	global_load_lds_dwordx4 v[180:181], off
	v_lshl_add_u64 v[180:181], v[208:209], 0, s[82:83]
	s_add_i32 m0, s4, 0x2000
	s_add_i32 s4, s7, s37
	global_load_lds_dwordx4 v[180:181], off
	v_lshl_add_u64 v[180:181], v[226:227], 0, s[82:83]
	s_mov_b32 m0, s4
	s_nop 0
	global_load_lds_dwordx4 v[180:181], off
	v_lshl_add_u64 v[180:181], v[228:229], 0, s[82:83]
	s_add_i32 m0, s4, 0x2000
	s_nop 0
	global_load_lds_dwordx4 v[180:181], off
	v_lshl_add_u64 v[180:181], v[230:231], 0, s[82:83]
	s_mov_b32 m0, s51
	s_nop 0
	global_load_lds_dwordx4 v[180:181], off
	v_lshl_add_u64 v[180:181], v[232:233], 0, s[82:83]
	s_mov_b32 m0, s52
	s_nop 0
	global_load_lds_dwordx4 v[180:181], off
	s_waitcnt vmcnt(8)
	s_waitcnt lgkmcnt(0)
	s_barrier
	s_setprio 1
	s_waitcnt lgkmcnt(0)
	v_mfma_f32_16x16x32_bf16 v[62:65], v[130:133], v[172:175], v[62:65]
	v_mfma_f32_16x16x32_bf16 v[58:61], v[138:141], v[172:175], v[58:61]
	v_mfma_f32_16x16x32_bf16 v[46:49], v[130:133], v[188:191], v[46:49]
	v_mfma_f32_16x16x32_bf16 v[42:45], v[138:141], v[188:191], v[42:45]
	v_mfma_f32_16x16x32_bf16 v[34:37], v[130:133], v[196:199], v[34:37]
	v_mfma_f32_16x16x32_bf16 v[26:29], v[138:141], v[196:199], v[26:29]
	v_mfma_f32_16x16x32_bf16 v[18:21], v[130:133], v[204:207], v[18:21]
	v_mfma_f32_16x16x32_bf16 v[10:13], v[138:141], v[204:207], v[10:13]
	v_mfma_f32_16x16x32_bf16 v[62:65], v[134:137], v[176:179], v[62:65]
	v_mfma_f32_16x16x32_bf16 v[58:61], v[142:145], v[176:179], v[58:61]
	v_mfma_f32_16x16x32_bf16 v[46:49], v[134:137], v[192:195], v[46:49]
	v_mfma_f32_16x16x32_bf16 v[42:45], v[142:145], v[192:195], v[42:45]
	v_mfma_f32_16x16x32_bf16 v[34:37], v[134:137], v[200:203], v[34:37]
	v_mfma_f32_16x16x32_bf16 v[26:29], v[142:145], v[200:203], v[26:29]
	v_mfma_f32_16x16x32_bf16 v[18:21], v[134:137], v[222:225], v[18:21]
	v_mfma_f32_16x16x32_bf16 v[10:13], v[142:145], v[222:225], v[10:13]
	v_mfma_f32_16x16x32_bf16 v[54:57], v[146:149], v[172:175], v[54:57]
	v_mfma_f32_16x16x32_bf16 v[50:53], v[154:157], v[172:175], v[50:53]
	v_mfma_f32_16x16x32_bf16 v[38:41], v[146:149], v[188:191], v[38:41]
	v_mfma_f32_16x16x32_bf16 v[30:33], v[154:157], v[188:191], v[30:33]
	v_mfma_f32_16x16x32_bf16 v[22:25], v[146:149], v[196:199], v[22:25]
	v_mfma_f32_16x16x32_bf16 v[14:17], v[154:157], v[196:199], v[14:17]
	v_mfma_f32_16x16x32_bf16 v[6:9], v[146:149], v[204:207], v[6:9]
	v_mfma_f32_16x16x32_bf16 v[2:5], v[154:157], v[204:207], v[2:5]
	v_mfma_f32_16x16x32_bf16 v[54:57], v[150:153], v[176:179], v[54:57]
	v_mfma_f32_16x16x32_bf16 v[50:53], v[168:171], v[176:179], v[50:53]
	v_mfma_f32_16x16x32_bf16 v[38:41], v[150:153], v[192:195], v[38:41]
	v_mfma_f32_16x16x32_bf16 v[30:33], v[168:171], v[192:195], v[30:33]
	v_mfma_f32_16x16x32_bf16 v[22:25], v[150:153], v[200:203], v[22:25]
	v_mfma_f32_16x16x32_bf16 v[14:17], v[168:171], v[200:203], v[14:17]
	v_mfma_f32_16x16x32_bf16 v[6:9], v[150:153], v[222:225], v[6:9]
	s_barrier
	v_mfma_f32_16x16x32_bf16 v[2:5], v[168:171], v[222:225], v[2:5]
	s_setprio 0
	s_add_u32 s30, s30, 0x100
	s_addc_u32 s31, s31, 0
	s_add_u32 s42, s42, 0x100
	s_addc_u32 s43, s43, 0
	s_cmp_ge_u32 s59, s48
	s_mov_b32 s34, s59
	s_cbranch_scc0 .LBB0_452
	s_and_b64 vcc, exec, s[24:25]
	s_cbranch_vccz .LBB0_455
	s_barrier

.LBB0_488:
	s_ashr_i32 s25, s24, 31
	s_lshl_b64 s[4:5], s[24:25], 19
	s_add_u32 s26, s12, s4
	s_addc_u32 s27, s13, s5
	s_and_b64 s[4:5], s[40:41], exec
	s_cselect_b32 s25, s27, s31
	s_cselect_b32 s66, s26, s30
	s_ashr_i32 s23, s22, 31
	s_lshl_b64 s[4:5], s[22:23], 19
	s_add_u32 s28, s39, s4
	s_addc_u32 s29, s42, s5
	s_and_b64 s[4:5], s[40:41], exec
	s_cselect_b32 s23, s29, s35
	s_cselect_b32 s67, s28, s34
	s_add_u32 s30, s30, 0x40080
	s_addc_u32 s31, s31, 0
	s_add_u32 s68, s34, 0x100
	v_mov_b32_e32 v2, 0
	s_addc_u32 s69, s35, 0
	s_mov_b32 s59, -2
	s_add_u32 s4, s30, 0xfffc0080
	s_addc_u32 s5, s31, -1
	s_add_i32 s6, 0, 0x10000
	s_cmp_eq_u32 s59, 12
	s_cselect_b32 s37, s25, s5
	s_cselect_b32 s36, s66, s4
	s_cselect_b32 s35, s23, s69
	s_cselect_b32 s34, s67, s68
	s_add_i32 s7, 0, 0x14000
	v_add_u32_e32 v156, s6, v146
	v_add_u32_e32 v172, s7, v146
	ds_read_b128 v[140:143], v156
	ds_read_b128 v[148:151], v156 offset:1024
	ds_read_b128 v[152:155], v156 offset:2048
	ds_read_b128 v[156:159], v156 offset:3072
	ds_read_b128 v[160:163], v172
	ds_read_b128 v[164:167], v172 offset:1024
	ds_read_b128 v[168:171], v172 offset:2048
	ds_read_b128 v[172:175], v172 offset:3072
	v_lshl_add_u64 v[208:209], s[30:31], 0, v[136:137]
	s_add_i32 m0, s43, 0xc000
	ds_read_b128 v[176:179], v147
	ds_read_b128 v[180:183], v147 offset:1024
	ds_read_b128 v[184:187], v147 offset:2048
	ds_read_b128 v[188:191], v147 offset:3072
	ds_read_b128 v[192:195], v147 offset:4096
	ds_read_b128 v[196:199], v147 offset:5120
	ds_read_b128 v[200:203], v147 offset:6144
	ds_read_b128 v[204:207], v147 offset:7168
	global_load_lds_dwordx4 v[208:209], off
	v_lshl_add_u64 v[208:209], s[30:31], 0, v[138:139]
	s_add_i32 m0, s43, 0xe000
	s_nop 0
	global_load_lds_dwordx4 v[208:209], off
	s_waitcnt vmcnt(24)
	s_waitcnt lgkmcnt(0)
	s_barrier
	s_setprio 1
	s_waitcnt lgkmcnt(0)
	v_mfma_f32_16x16x32_bf16 v[126:129], v[140:143], v[176:179], 0
	v_mfma_f32_16x16x32_bf16 v[122:125], v[152:155], v[176:179], 0
	v_mfma_f32_16x16x32_bf16 v[118:121], v[140:143], v[184:187], 0
	v_mfma_f32_16x16x32_bf16 v[110:113], v[152:155], v[184:187], 0
	v_mfma_f32_16x16x32_bf16 v[102:105], v[140:143], v[192:195], 0
	v_mfma_f32_16x16x32_bf16 v[94:97], v[152:155], v[192:195], 0
	v_mfma_f32_16x16x32_bf16 v[86:89], v[140:143], v[200:203], 0
	v_mfma_f32_16x16x32_bf16 v[78:81], v[152:155], v[200:203], 0
	v_mfma_f32_16x16x32_bf16 v[126:129], v[148:151], v[180:183], v[126:129]
	v_mfma_f32_16x16x32_bf16 v[122:125], v[156:159], v[180:183], v[122:125]
	v_mfma_f32_16x16x32_bf16 v[118:121], v[148:151], v[188:191], v[118:121]
	v_mfma_f32_16x16x32_bf16 v[110:113], v[156:159], v[188:191], v[110:113]
	v_mfma_f32_16x16x32_bf16 v[102:105], v[148:151], v[196:199], v[102:105]
	v_mfma_f32_16x16x32_bf16 v[94:97], v[156:159], v[196:199], v[94:97]
	v_mfma_f32_16x16x32_bf16 v[86:89], v[148:151], v[204:207], v[86:89]
	v_mfma_f32_16x16x32_bf16 v[78:81], v[156:159], v[204:207], v[78:81]
	v_mfma_f32_16x16x32_bf16 v[114:117], v[160:163], v[176:179], 0
	v_mfma_f32_16x16x32_bf16 v[106:109], v[168:171], v[176:179], 0
	v_mfma_f32_16x16x32_bf16 v[98:101], v[160:163], v[184:187], 0
	v_mfma_f32_16x16x32_bf16 v[90:93], v[168:171], v[184:187], 0
	v_mfma_f32_16x16x32_bf16 v[82:85], v[160:163], v[192:195], 0
	v_mfma_f32_16x16x32_bf16 v[74:77], v[168:171], v[192:195], 0
	v_mfma_f32_16x16x32_bf16 v[70:73], v[160:163], v[200:203], 0
	v_mfma_f32_16x16x32_bf16 v[66:69], v[168:171], v[200:203], 0
	v_mfma_f32_16x16x32_bf16 v[114:117], v[164:167], v[180:183], v[114:117]
	v_mfma_f32_16x16x32_bf16 v[106:109], v[172:175], v[180:183], v[106:109]
	v_mfma_f32_16x16x32_bf16 v[98:101], v[164:167], v[188:191], v[98:101]
	v_mfma_f32_16x16x32_bf16 v[90:93], v[172:175], v[188:191], v[90:93]
	v_mfma_f32_16x16x32_bf16 v[82:85], v[164:167], v[196:199], v[82:85]
	v_mfma_f32_16x16x32_bf16 v[74:77], v[172:175], v[196:199], v[74:77]
	v_mfma_f32_16x16x32_bf16 v[70:73], v[164:167], v[204:207], v[70:73]
	s_barrier
	v_mfma_f32_16x16x32_bf16 v[66:69], v[172:175], v[204:207], v[66:69]
	s_setprio 0
	s_add_i32 s4, s6, s38
	v_lshl_add_u64 v[208:209], s[34:35], 0, v[0:1]
	s_mov_b32 m0, s4
	ds_read_b128 v[176:179], v147 offset:16384
	ds_read_b128 v[180:183], v147 offset:17408
	ds_read_b128 v[184:187], v147 offset:18432
	ds_read_b128 v[188:191], v147 offset:19456
	ds_read_b128 v[192:195], v147 offset:20480
	ds_read_b128 v[196:199], v147 offset:21504
	ds_read_b128 v[200:203], v147 offset:22528
	ds_read_b128 v[204:207], v147 offset:23552
	global_load_lds_dwordx4 v[208:209], off
	s_add_i32 m0, s4, 0x2000
	s_add_u32 s4, s34, 0x40000
	v_lshl_add_u64 v[222:223], s[34:35], 0, v[132:133]
	s_addc_u32 s5, s35, 0
	s_add_i32 s6, s7, s38
	global_load_lds_dwordx4 v[222:223], off
	v_lshl_add_u64 v[224:225], s[4:5], 0, v[0:1]
	s_mov_b32 m0, s6
	v_lshl_add_u64 v[226:227], s[36:37], 0, v[130:131]
	global_load_lds_dwordx4 v[224:225], off
	v_lshl_add_u64 v[224:225], s[4:5], 0, v[132:133]
	s_add_i32 m0, s6, 0x2000
	s_nop 0
	global_load_lds_dwordx4 v[224:225], off
	v_lshl_add_u64 v[224:225], s[36:37], 0, v[134:135]
	s_mov_b32 m0, s43
	s_nop 0
	global_load_lds_dwordx4 v[224:225], off
	s_mov_b32 m0, s44
	s_nop 0
	global_load_lds_dwordx4 v[226:227], off
	s_waitcnt vmcnt(24)
	s_waitcnt lgkmcnt(0)
	s_barrier
	s_setprio 1
	s_waitcnt lgkmcnt(0)
	v_mfma_f32_16x16x32_bf16 v[62:65], v[140:143], v[176:179], 0
	v_mfma_f32_16x16x32_bf16 v[58:61], v[152:155], v[176:179], 0
	v_mfma_f32_16x16x32_bf16 v[54:57], v[140:143], v[184:187], 0
	v_mfma_f32_16x16x32_bf16 v[46:49], v[152:155], v[184:187], 0
	v_mfma_f32_16x16x32_bf16 v[38:41], v[140:143], v[192:195], 0
	v_mfma_f32_16x16x32_bf16 v[30:33], v[152:155], v[192:195], 0
	v_mfma_f32_16x16x32_bf16 v[22:25], v[140:143], v[200:203], 0
	v_mfma_f32_16x16x32_bf16 v[14:17], v[152:155], v[200:203], 0
	v_mfma_f32_16x16x32_bf16 v[62:65], v[148:151], v[180:183], v[62:65]
	v_mfma_f32_16x16x32_bf16 v[58:61], v[156:159], v[180:183], v[58:61]
	v_mfma_f32_16x16x32_bf16 v[54:57], v[148:151], v[188:191], v[54:57]
	v_mfma_f32_16x16x32_bf16 v[46:49], v[156:159], v[188:191], v[46:49]
	v_mfma_f32_16x16x32_bf16 v[38:41], v[148:151], v[196:199], v[38:41]
	v_mfma_f32_16x16x32_bf16 v[30:33], v[156:159], v[196:199], v[30:33]
	v_mfma_f32_16x16x32_bf16 v[22:25], v[148:151], v[204:207], v[22:25]
	v_mfma_f32_16x16x32_bf16 v[14:17], v[156:159], v[204:207], v[14:17]
	v_mfma_f32_16x16x32_bf16 v[50:53], v[160:163], v[176:179], 0
	v_mfma_f32_16x16x32_bf16 v[42:45], v[168:171], v[176:179], 0
	v_mfma_f32_16x16x32_bf16 v[34:37], v[160:163], v[184:187], 0
	v_mfma_f32_16x16x32_bf16 v[26:29], v[168:171], v[184:187], 0
	v_mfma_f32_16x16x32_bf16 v[18:21], v[160:163], v[192:195], 0
	v_mfma_f32_16x16x32_bf16 v[10:13], v[168:171], v[192:195], 0
	v_mfma_f32_16x16x32_bf16 v[6:9], v[160:163], v[200:203], 0
	v_mfma_f32_16x16x32_bf16 v[2:5], v[168:171], v[200:203], 0
	v_mfma_f32_16x16x32_bf16 v[50:53], v[164:167], v[180:183], v[50:53]
	v_mfma_f32_16x16x32_bf16 v[42:45], v[172:175], v[180:183], v[42:45]
	v_mfma_f32_16x16x32_bf16 v[34:37], v[164:167], v[188:191], v[34:37]
	v_mfma_f32_16x16x32_bf16 v[26:29], v[172:175], v[188:191], v[26:29]
	v_mfma_f32_16x16x32_bf16 v[18:21], v[164:167], v[196:199], v[18:21]
	v_mfma_f32_16x16x32_bf16 v[10:13], v[172:175], v[196:199], v[10:13]
	v_mfma_f32_16x16x32_bf16 v[6:9], v[164:167], v[204:207], v[6:9]
	s_barrier
	v_mfma_f32_16x16x32_bf16 v[2:5], v[172:175], v[204:207], v[2:5]
	s_setprio 0
	s_add_i32 s6, 0, 0x18000
	s_add_i32 s7, 0, 0x1c000
	v_add_u32_e32 v156, s6, v146
	v_add_u32_e32 v172, s7, v146
	ds_read_b128 v[140:143], v156
	ds_read_b128 v[148:151], v156 offset:1024
	ds_read_b128 v[152:155], v156 offset:2048
	ds_read_b128 v[156:159], v156 offset:3072
	ds_read_b128 v[160:163], v172
	ds_read_b128 v[164:167], v172 offset:1024
	ds_read_b128 v[168:171], v172 offset:2048
	ds_read_b128 v[172:175], v172 offset:3072
	s_add_u32 s4, s36, 0x40000
	s_addc_u32 s5, s37, 0
	s_mov_b32 m0, s45
	v_lshl_add_u64 v[228:229], s[4:5], 0, v[134:135]
	ds_read_b128 v[176:179], v147 offset:32768
	ds_read_b128 v[180:183], v147 offset:33792
	ds_read_b128 v[184:187], v147 offset:34816
	ds_read_b128 v[188:191], v147 offset:35840
	ds_read_b128 v[192:195], v147 offset:36864
	ds_read_b128 v[196:199], v147 offset:37888
	ds_read_b128 v[200:203], v147 offset:38912
	ds_read_b128 v[204:207], v147 offset:39936
	global_load_lds_dwordx4 v[228:229], off
	v_lshl_add_u64 v[228:229], s[4:5], 0, v[130:131]
	s_mov_b32 m0, s46
	s_nop 0
	global_load_lds_dwordx4 v[228:229], off
	s_waitcnt vmcnt(8)
	s_waitcnt lgkmcnt(0)
	s_barrier
	s_setprio 1
	s_waitcnt lgkmcnt(0)
	v_mfma_f32_16x16x32_bf16 v[126:129], v[140:143], v[176:179], v[126:129]
	v_mfma_f32_16x16x32_bf16 v[122:125], v[152:155], v[176:179], v[122:125]
	v_mfma_f32_16x16x32_bf16 v[118:121], v[140:143], v[184:187], v[118:121]
	v_mfma_f32_16x16x32_bf16 v[110:113], v[152:155], v[184:187], v[110:113]
	v_mfma_f32_16x16x32_bf16 v[102:105], v[140:143], v[192:195], v[102:105]
	v_mfma_f32_16x16x32_bf16 v[94:97], v[152:155], v[192:195], v[94:97]
	v_mfma_f32_16x16x32_bf16 v[86:89], v[140:143], v[200:203], v[86:89]
	v_mfma_f32_16x16x32_bf16 v[78:81], v[152:155], v[200:203], v[78:81]
	v_mfma_f32_16x16x32_bf16 v[126:129], v[148:151], v[180:183], v[126:129]
	v_mfma_f32_16x16x32_bf16 v[122:125], v[156:159], v[180:183], v[122:125]
	v_mfma_f32_16x16x32_bf16 v[118:121], v[148:151], v[188:191], v[118:121]
	v_mfma_f32_16x16x32_bf16 v[110:113], v[156:159], v[188:191], v[110:113]
	v_mfma_f32_16x16x32_bf16 v[102:105], v[148:151], v[196:199], v[102:105]
	v_mfma_f32_16x16x32_bf16 v[94:97], v[156:159], v[196:199], v[94:97]
	v_mfma_f32_16x16x32_bf16 v[86:89], v[148:151], v[204:207], v[86:89]
	v_mfma_f32_16x16x32_bf16 v[78:81], v[156:159], v[204:207], v[78:81]
	v_mfma_f32_16x16x32_bf16 v[114:117], v[160:163], v[176:179], v[114:117]
	v_mfma_f32_16x16x32_bf16 v[106:109], v[168:171], v[176:179], v[106:109]
	v_mfma_f32_16x16x32_bf16 v[98:101], v[160:163], v[184:187], v[98:101]
	v_mfma_f32_16x16x32_bf16 v[90:93], v[168:171], v[184:187], v[90:93]
	v_mfma_f32_16x16x32_bf16 v[82:85], v[160:163], v[192:195], v[82:85]
	v_mfma_f32_16x16x32_bf16 v[74:77], v[168:171], v[192:195], v[74:77]
	v_mfma_f32_16x16x32_bf16 v[70:73], v[160:163], v[200:203], v[70:73]
	v_mfma_f32_16x16x32_bf16 v[66:69], v[168:171], v[200:203], v[66:69]
	v_mfma_f32_16x16x32_bf16 v[114:117], v[164:167], v[180:183], v[114:117]
	v_mfma_f32_16x16x32_bf16 v[106:109], v[172:175], v[180:183], v[106:109]
	v_mfma_f32_16x16x32_bf16 v[98:101], v[164:167], v[188:191], v[98:101]
	v_mfma_f32_16x16x32_bf16 v[90:93], v[172:175], v[188:191], v[90:93]
	v_mfma_f32_16x16x32_bf16 v[82:85], v[164:167], v[196:199], v[82:85]
	v_mfma_f32_16x16x32_bf16 v[74:77], v[172:175], v[196:199], v[74:77]
	v_mfma_f32_16x16x32_bf16 v[70:73], v[164:167], v[204:207], v[70:73]
	s_barrier
	v_mfma_f32_16x16x32_bf16 v[66:69], v[172:175], v[204:207], v[66:69]
	s_setprio 0
	s_add_i32 s4, s6, s38
	v_lshl_add_u64 v[208:209], v[208:209], 0, s[82:83]
	s_mov_b32 m0, s4
	ds_read_b128 v[176:179], v147 offset:49152
	ds_read_b128 v[180:183], v147 offset:50176
	ds_read_b128 v[184:187], v147 offset:51200
	ds_read_b128 v[188:191], v147 offset:52224
	ds_read_b128 v[192:195], v147 offset:53248
	ds_read_b128 v[196:199], v147 offset:54272
	ds_read_b128 v[200:203], v147 offset:55296
	ds_read_b128 v[204:207], v147 offset:56320
	global_load_lds_dwordx4 v[208:209], off
	s_add_i32 m0, s4, 0x2000
	s_add_u32 s4, s34, 0x40080
	v_lshl_add_u64 v[208:209], v[222:223], 0, s[82:83]
	s_addc_u32 s5, s35, 0
	s_add_i32 s6, s7, s38
	global_load_lds_dwordx4 v[208:209], off
	v_lshl_add_u64 v[208:209], s[4:5], 0, v[0:1]
	s_mov_b32 m0, s6
	s_nop 0
	global_load_lds_dwordx4 v[208:209], off
	v_lshl_add_u64 v[208:209], s[4:5], 0, v[132:133]
	s_add_i32 m0, s6, 0x2000
	s_nop 0
	global_load_lds_dwordx4 v[208:209], off
	v_lshl_add_u64 v[208:209], v[224:225], 0, s[82:83]
	s_mov_b32 m0, s49
	s_nop 0
	global_load_lds_dwordx4 v[208:209], off
	v_lshl_add_u64 v[208:209], v[226:227], 0, s[82:83]
	s_mov_b32 m0, s50
	s_nop 0
	global_load_lds_dwordx4 v[208:209], off
	s_waitcnt vmcnt(8)
	s_waitcnt lgkmcnt(0)
	s_barrier
	s_setprio 1
	s_waitcnt lgkmcnt(0)
	v_mfma_f32_16x16x32_bf16 v[62:65], v[140:143], v[176:179], v[62:65]
	v_mfma_f32_16x16x32_bf16 v[58:61], v[152:155], v[176:179], v[58:61]
	v_mfma_f32_16x16x32_bf16 v[54:57], v[140:143], v[184:187], v[54:57]
	v_mfma_f32_16x16x32_bf16 v[46:49], v[152:155], v[184:187], v[46:49]
	v_mfma_f32_16x16x32_bf16 v[38:41], v[140:143], v[192:195], v[38:41]
	v_mfma_f32_16x16x32_bf16 v[30:33], v[152:155], v[192:195], v[30:33]
	v_mfma_f32_16x16x32_bf16 v[22:25], v[140:143], v[200:203], v[22:25]
	v_mfma_f32_16x16x32_bf16 v[14:17], v[152:155], v[200:203], v[14:17]
	v_mfma_f32_16x16x32_bf16 v[62:65], v[148:151], v[180:183], v[62:65]
	v_mfma_f32_16x16x32_bf16 v[58:61], v[156:159], v[180:183], v[58:61]
	v_mfma_f32_16x16x32_bf16 v[54:57], v[148:151], v[188:191], v[54:57]
	v_mfma_f32_16x16x32_bf16 v[46:49], v[156:159], v[188:191], v[46:49]
	v_mfma_f32_16x16x32_bf16 v[38:41], v[148:151], v[196:199], v[38:41]
	v_mfma_f32_16x16x32_bf16 v[30:33], v[156:159], v[196:199], v[30:33]
	v_mfma_f32_16x16x32_bf16 v[22:25], v[148:151], v[204:207], v[22:25]
	v_mfma_f32_16x16x32_bf16 v[14:17], v[156:159], v[204:207], v[14:17]
	v_mfma_f32_16x16x32_bf16 v[50:53], v[160:163], v[176:179], v[50:53]
	v_mfma_f32_16x16x32_bf16 v[42:45], v[168:171], v[176:179], v[42:45]
	v_mfma_f32_16x16x32_bf16 v[34:37], v[160:163], v[184:187], v[34:37]
	v_mfma_f32_16x16x32_bf16 v[26:29], v[168:171], v[184:187], v[26:29]
	v_mfma_f32_16x16x32_bf16 v[18:21], v[160:163], v[192:195], v[18:21]
	v_mfma_f32_16x16x32_bf16 v[10:13], v[168:171], v[192:195], v[10:13]
	v_mfma_f32_16x16x32_bf16 v[6:9], v[160:163], v[200:203], v[6:9]
	v_mfma_f32_16x16x32_bf16 v[2:5], v[168:171], v[200:203], v[2:5]
	v_mfma_f32_16x16x32_bf16 v[50:53], v[164:167], v[180:183], v[50:53]
	v_mfma_f32_16x16x32_bf16 v[42:45], v[172:175], v[180:183], v[42:45]
	v_mfma_f32_16x16x32_bf16 v[34:37], v[164:167], v[188:191], v[34:37]
	v_mfma_f32_16x16x32_bf16 v[26:29], v[172:175], v[188:191], v[26:29]
	v_mfma_f32_16x16x32_bf16 v[18:21], v[164:167], v[196:199], v[18:21]
	v_mfma_f32_16x16x32_bf16 v[10:13], v[172:175], v[196:199], v[10:13]
	v_mfma_f32_16x16x32_bf16 v[6:9], v[164:167], v[204:207], v[6:9]
	s_barrier
	v_mfma_f32_16x16x32_bf16 v[2:5], v[172:175], v[204:207], v[2:5]
	s_setprio 0
	s_add_i32 s59, s59, 2
	s_add_u32 s30, s30, 0x100
	s_addc_u32 s31, s31, 0
	s_add_u32 s68, s68, 0x100
	s_addc_u32 s69, s69, 0
	s_cmp_gt_u32 s59, 13
.LBB0_489:
	s_add_u32 s4, s30, 0xfffc0080
	s_addc_u32 s5, s31, -1
	s_add_i32 s6, 0, 0x10000
	s_cmp_eq_u32 s59, 12
	s_cselect_b32 s37, s25, s5
	s_cselect_b32 s36, s66, s4
	s_cselect_b32 s35, s23, s69
	s_cselect_b32 s34, s67, s68
	s_add_i32 s7, 0, 0x14000
	v_add_u32_e32 v156, s6, v146
	v_add_u32_e32 v172, s7, v146
	ds_read_b128 v[140:143], v156
	ds_read_b128 v[148:151], v156 offset:1024
	ds_read_b128 v[152:155], v156 offset:2048
	ds_read_b128 v[156:159], v156 offset:3072
	ds_read_b128 v[160:163], v172
	ds_read_b128 v[164:167], v172 offset:1024
	ds_read_b128 v[168:171], v172 offset:2048
	ds_read_b128 v[172:175], v172 offset:3072
	v_lshl_add_u64 v[208:209], s[30:31], 0, v[136:137]
	s_add_i32 m0, s43, 0xc000
	ds_read_b128 v[176:179], v147
	ds_read_b128 v[180:183], v147 offset:1024
	ds_read_b128 v[184:187], v147 offset:2048
	ds_read_b128 v[188:191], v147 offset:3072
	ds_read_b128 v[192:195], v147 offset:4096
	ds_read_b128 v[196:199], v147 offset:5120
	ds_read_b128 v[200:203], v147 offset:6144
	ds_read_b128 v[204:207], v147 offset:7168
	global_load_lds_dwordx4 v[208:209], off
	v_lshl_add_u64 v[208:209], s[30:31], 0, v[138:139]
	s_add_i32 m0, s43, 0xe000
	s_nop 0
	global_load_lds_dwordx4 v[208:209], off
	s_waitcnt vmcnt(8)
	s_waitcnt lgkmcnt(0)
	s_barrier
	s_setprio 1
	s_waitcnt lgkmcnt(0)
	v_mfma_f32_16x16x32_bf16 v[126:129], v[140:143], v[176:179], v[126:129]
	v_mfma_f32_16x16x32_bf16 v[122:125], v[152:155], v[176:179], v[122:125]
	v_mfma_f32_16x16x32_bf16 v[118:121], v[140:143], v[184:187], v[118:121]
	v_mfma_f32_16x16x32_bf16 v[110:113], v[152:155], v[184:187], v[110:113]
	v_mfma_f32_16x16x32_bf16 v[102:105], v[140:143], v[192:195], v[102:105]
	v_mfma_f32_16x16x32_bf16 v[94:97], v[152:155], v[192:195], v[94:97]
	v_mfma_f32_16x16x32_bf16 v[86:89], v[140:143], v[200:203], v[86:89]
	v_mfma_f32_16x16x32_bf16 v[78:81], v[152:155], v[200:203], v[78:81]
	v_mfma_f32_16x16x32_bf16 v[126:129], v[148:151], v[180:183], v[126:129]
	v_mfma_f32_16x16x32_bf16 v[122:125], v[156:159], v[180:183], v[122:125]
	v_mfma_f32_16x16x32_bf16 v[118:121], v[148:151], v[188:191], v[118:121]
	v_mfma_f32_16x16x32_bf16 v[110:113], v[156:159], v[188:191], v[110:113]
	v_mfma_f32_16x16x32_bf16 v[102:105], v[148:151], v[196:199], v[102:105]
	v_mfma_f32_16x16x32_bf16 v[94:97], v[156:159], v[196:199], v[94:97]
	v_mfma_f32_16x16x32_bf16 v[86:89], v[148:151], v[204:207], v[86:89]
	v_mfma_f32_16x16x32_bf16 v[78:81], v[156:159], v[204:207], v[78:81]
	v_mfma_f32_16x16x32_bf16 v[114:117], v[160:163], v[176:179], v[114:117]
	v_mfma_f32_16x16x32_bf16 v[106:109], v[168:171], v[176:179], v[106:109]
	v_mfma_f32_16x16x32_bf16 v[98:101], v[160:163], v[184:187], v[98:101]
	v_mfma_f32_16x16x32_bf16 v[90:93], v[168:171], v[184:187], v[90:93]
	v_mfma_f32_16x16x32_bf16 v[82:85], v[160:163], v[192:195], v[82:85]
	v_mfma_f32_16x16x32_bf16 v[74:77], v[168:171], v[192:195], v[74:77]
	v_mfma_f32_16x16x32_bf16 v[70:73], v[160:163], v[200:203], v[70:73]
	v_mfma_f32_16x16x32_bf16 v[66:69], v[168:171], v[200:203], v[66:69]
	v_mfma_f32_16x16x32_bf16 v[114:117], v[164:167], v[180:183], v[114:117]
	v_mfma_f32_16x16x32_bf16 v[106:109], v[172:175], v[180:183], v[106:109]
	v_mfma_f32_16x16x32_bf16 v[98:101], v[164:167], v[188:191], v[98:101]
	v_mfma_f32_16x16x32_bf16 v[90:93], v[172:175], v[188:191], v[90:93]
	v_mfma_f32_16x16x32_bf16 v[82:85], v[164:167], v[196:199], v[82:85]
	v_mfma_f32_16x16x32_bf16 v[74:77], v[172:175], v[196:199], v[74:77]
	v_mfma_f32_16x16x32_bf16 v[70:73], v[164:167], v[204:207], v[70:73]
	s_barrier
	v_mfma_f32_16x16x32_bf16 v[66:69], v[172:175], v[204:207], v[66:69]
	s_setprio 0
	s_add_i32 s4, s6, s38
	v_lshl_add_u64 v[208:209], s[34:35], 0, v[0:1]
	s_mov_b32 m0, s4
	ds_read_b128 v[176:179], v147 offset:16384
	ds_read_b128 v[180:183], v147 offset:17408
	ds_read_b128 v[184:187], v147 offset:18432
	ds_read_b128 v[188:191], v147 offset:19456
	ds_read_b128 v[192:195], v147 offset:20480
	ds_read_b128 v[196:199], v147 offset:21504
	ds_read_b128 v[200:203], v147 offset:22528
	ds_read_b128 v[204:207], v147 offset:23552
	global_load_lds_dwordx4 v[208:209], off
	s_add_i32 m0, s4, 0x2000
	s_add_u32 s4, s34, 0x40000
	v_lshl_add_u64 v[222:223], s[34:35], 0, v[132:133]
	s_addc_u32 s5, s35, 0
	s_add_i32 s6, s7, s38
	global_load_lds_dwordx4 v[222:223], off
	v_lshl_add_u64 v[224:225], s[4:5], 0, v[0:1]
	s_mov_b32 m0, s6
	v_lshl_add_u64 v[226:227], s[36:37], 0, v[130:131]
	global_load_lds_dwordx4 v[224:225], off
	v_lshl_add_u64 v[224:225], s[4:5], 0, v[132:133]
	s_add_i32 m0, s6, 0x2000
	s_nop 0
	global_load_lds_dwordx4 v[224:225], off
	v_lshl_add_u64 v[224:225], s[36:37], 0, v[134:135]
	s_mov_b32 m0, s43
	s_nop 0
	global_load_lds_dwordx4 v[224:225], off
	s_mov_b32 m0, s44
	s_nop 0
	global_load_lds_dwordx4 v[226:227], off
	s_waitcnt vmcnt(8)
	s_waitcnt lgkmcnt(0)
	s_barrier
	s_setprio 1
	s_waitcnt lgkmcnt(0)
	v_mfma_f32_16x16x32_bf16 v[62:65], v[140:143], v[176:179], v[62:65]
	v_mfma_f32_16x16x32_bf16 v[58:61], v[152:155], v[176:179], v[58:61]
	v_mfma_f32_16x16x32_bf16 v[54:57], v[140:143], v[184:187], v[54:57]
	v_mfma_f32_16x16x32_bf16 v[46:49], v[152:155], v[184:187], v[46:49]
	v_mfma_f32_16x16x32_bf16 v[38:41], v[140:143], v[192:195], v[38:41]
	v_mfma_f32_16x16x32_bf16 v[30:33], v[152:155], v[192:195], v[30:33]
	v_mfma_f32_16x16x32_bf16 v[22:25], v[140:143], v[200:203], v[22:25]
	v_mfma_f32_16x16x32_bf16 v[14:17], v[152:155], v[200:203], v[14:17]
	v_mfma_f32_16x16x32_bf16 v[62:65], v[148:151], v[180:183], v[62:65]
	v_mfma_f32_16x16x32_bf16 v[58:61], v[156:159], v[180:183], v[58:61]
	v_mfma_f32_16x16x32_bf16 v[54:57], v[148:151], v[188:191], v[54:57]
	v_mfma_f32_16x16x32_bf16 v[46:49], v[156:159], v[188:191], v[46:49]
	v_mfma_f32_16x16x32_bf16 v[38:41], v[148:151], v[196:199], v[38:41]
	v_mfma_f32_16x16x32_bf16 v[30:33], v[156:159], v[196:199], v[30:33]
	v_mfma_f32_16x16x32_bf16 v[22:25], v[148:151], v[204:207], v[22:25]
	v_mfma_f32_16x16x32_bf16 v[14:17], v[156:159], v[204:207], v[14:17]
	v_mfma_f32_16x16x32_bf16 v[50:53], v[160:163], v[176:179], v[50:53]
	v_mfma_f32_16x16x32_bf16 v[42:45], v[168:171], v[176:179], v[42:45]
	v_mfma_f32_16x16x32_bf16 v[34:37], v[160:163], v[184:187], v[34:37]
	v_mfma_f32_16x16x32_bf16 v[26:29], v[168:171], v[184:187], v[26:29]
	v_mfma_f32_16x16x32_bf16 v[18:21], v[160:163], v[192:195], v[18:21]
	v_mfma_f32_16x16x32_bf16 v[10:13], v[168:171], v[192:195], v[10:13]
	v_mfma_f32_16x16x32_bf16 v[6:9], v[160:163], v[200:203], v[6:9]
	v_mfma_f32_16x16x32_bf16 v[2:5], v[168:171], v[200:203], v[2:5]
	v_mfma_f32_16x16x32_bf16 v[50:53], v[164:167], v[180:183], v[50:53]
	v_mfma_f32_16x16x32_bf16 v[42:45], v[172:175], v[180:183], v[42:45]
	v_mfma_f32_16x16x32_bf16 v[34:37], v[164:167], v[188:191], v[34:37]
	v_mfma_f32_16x16x32_bf16 v[26:29], v[172:175], v[188:191], v[26:29]
	v_mfma_f32_16x16x32_bf16 v[18:21], v[164:167], v[196:199], v[18:21]
	v_mfma_f32_16x16x32_bf16 v[10:13], v[172:175], v[196:199], v[10:13]
	v_mfma_f32_16x16x32_bf16 v[6:9], v[164:167], v[204:207], v[6:9]
	s_barrier
	v_mfma_f32_16x16x32_bf16 v[2:5], v[172:175], v[204:207], v[2:5]
	s_setprio 0
	s_add_i32 s6, 0, 0x18000
	s_add_i32 s7, 0, 0x1c000
	v_add_u32_e32 v156, s6, v146
	v_add_u32_e32 v172, s7, v146
	ds_read_b128 v[140:143], v156
	ds_read_b128 v[148:151], v156 offset:1024
	ds_read_b128 v[152:155], v156 offset:2048
	ds_read_b128 v[156:159], v156 offset:3072
	ds_read_b128 v[160:163], v172
	ds_read_b128 v[164:167], v172 offset:1024
	ds_read_b128 v[168:171], v172 offset:2048
	ds_read_b128 v[172:175], v172 offset:3072
	s_add_u32 s4, s36, 0x40000
	s_addc_u32 s5, s37, 0
	s_mov_b32 m0, s45
	v_lshl_add_u64 v[228:229], s[4:5], 0, v[134:135]
	ds_read_b128 v[176:179], v147 offset:32768
	ds_read_b128 v[180:183], v147 offset:33792
	ds_read_b128 v[184:187], v147 offset:34816
	ds_read_b128 v[188:191], v147 offset:35840
	ds_read_b128 v[192:195], v147 offset:36864
	ds_read_b128 v[196:199], v147 offset:37888
	ds_read_b128 v[200:203], v147 offset:38912
	ds_read_b128 v[204:207], v147 offset:39936
	global_load_lds_dwordx4 v[228:229], off
	v_lshl_add_u64 v[228:229], s[4:5], 0, v[130:131]
	s_mov_b32 m0, s46
	s_nop 0
	global_load_lds_dwordx4 v[228:229], off
	s_waitcnt vmcnt(8)
	s_waitcnt lgkmcnt(0)
	s_barrier
	s_setprio 1
	s_waitcnt lgkmcnt(0)
	v_mfma_f32_16x16x32_bf16 v[126:129], v[140:143], v[176:179], v[126:129]
	v_mfma_f32_16x16x32_bf16 v[122:125], v[152:155], v[176:179], v[122:125]
	v_mfma_f32_16x16x32_bf16 v[118:121], v[140:143], v[184:187], v[118:121]
	v_mfma_f32_16x16x32_bf16 v[110:113], v[152:155], v[184:187], v[110:113]
	v_mfma_f32_16x16x32_bf16 v[102:105], v[140:143], v[192:195], v[102:105]
	v_mfma_f32_16x16x32_bf16 v[94:97], v[152:155], v[192:195], v[94:97]
	v_mfma_f32_16x16x32_bf16 v[86:89], v[140:143], v[200:203], v[86:89]
	v_mfma_f32_16x16x32_bf16 v[78:81], v[152:155], v[200:203], v[78:81]
	v_mfma_f32_16x16x32_bf16 v[126:129], v[148:151], v[180:183], v[126:129]
	v_mfma_f32_16x16x32_bf16 v[122:125], v[156:159], v[180:183], v[122:125]
	v_mfma_f32_16x16x32_bf16 v[118:121], v[148:151], v[188:191], v[118:121]
	v_mfma_f32_16x16x32_bf16 v[110:113], v[156:159], v[188:191], v[110:113]
	v_mfma_f32_16x16x32_bf16 v[102:105], v[148:151], v[196:199], v[102:105]
	v_mfma_f32_16x16x32_bf16 v[94:97], v[156:159], v[196:199], v[94:97]
	v_mfma_f32_16x16x32_bf16 v[86:89], v[148:151], v[204:207], v[86:89]
	v_mfma_f32_16x16x32_bf16 v[78:81], v[156:159], v[204:207], v[78:81]
	v_mfma_f32_16x16x32_bf16 v[114:117], v[160:163], v[176:179], v[114:117]
	v_mfma_f32_16x16x32_bf16 v[106:109], v[168:171], v[176:179], v[106:109]
	v_mfma_f32_16x16x32_bf16 v[98:101], v[160:163], v[184:187], v[98:101]
	v_mfma_f32_16x16x32_bf16 v[90:93], v[168:171], v[184:187], v[90:93]
	v_mfma_f32_16x16x32_bf16 v[82:85], v[160:163], v[192:195], v[82:85]
	v_mfma_f32_16x16x32_bf16 v[74:77], v[168:171], v[192:195], v[74:77]
	v_mfma_f32_16x16x32_bf16 v[70:73], v[160:163], v[200:203], v[70:73]
	v_mfma_f32_16x16x32_bf16 v[66:69], v[168:171], v[200:203], v[66:69]
	v_mfma_f32_16x16x32_bf16 v[114:117], v[164:167], v[180:183], v[114:117]
	v_mfma_f32_16x16x32_bf16 v[106:109], v[172:175], v[180:183], v[106:109]
	v_mfma_f32_16x16x32_bf16 v[98:101], v[164:167], v[188:191], v[98:101]
	v_mfma_f32_16x16x32_bf16 v[90:93], v[172:175], v[188:191], v[90:93]
	v_mfma_f32_16x16x32_bf16 v[82:85], v[164:167], v[196:199], v[82:85]
	v_mfma_f32_16x16x32_bf16 v[74:77], v[172:175], v[196:199], v[74:77]
	v_mfma_f32_16x16x32_bf16 v[70:73], v[164:167], v[204:207], v[70:73]
	s_barrier
	v_mfma_f32_16x16x32_bf16 v[66:69], v[172:175], v[204:207], v[66:69]
	s_setprio 0
	s_add_i32 s4, s6, s38
	v_lshl_add_u64 v[208:209], v[208:209], 0, s[82:83]
	s_mov_b32 m0, s4
	ds_read_b128 v[176:179], v147 offset:49152
	ds_read_b128 v[180:183], v147 offset:50176
	ds_read_b128 v[184:187], v147 offset:51200
	ds_read_b128 v[188:191], v147 offset:52224
	ds_read_b128 v[192:195], v147 offset:53248
	ds_read_b128 v[196:199], v147 offset:54272
	ds_read_b128 v[200:203], v147 offset:55296
	ds_read_b128 v[204:207], v147 offset:56320
	global_load_lds_dwordx4 v[208:209], off
	s_add_i32 m0, s4, 0x2000
	s_add_u32 s4, s34, 0x40080
	v_lshl_add_u64 v[208:209], v[222:223], 0, s[82:83]
	s_addc_u32 s5, s35, 0
	s_add_i32 s6, s7, s38
	global_load_lds_dwordx4 v[208:209], off
	v_lshl_add_u64 v[208:209], s[4:5], 0, v[0:1]
	s_mov_b32 m0, s6
	s_nop 0
	global_load_lds_dwordx4 v[208:209], off
	v_lshl_add_u64 v[208:209], s[4:5], 0, v[132:133]
	s_add_i32 m0, s6, 0x2000
	s_nop 0
	global_load_lds_dwordx4 v[208:209], off
	v_lshl_add_u64 v[208:209], v[224:225], 0, s[82:83]
	s_mov_b32 m0, s49
	s_nop 0
	global_load_lds_dwordx4 v[208:209], off
	v_lshl_add_u64 v[208:209], v[226:227], 0, s[82:83]
	s_mov_b32 m0, s50
	s_nop 0
	global_load_lds_dwordx4 v[208:209], off
	s_waitcnt vmcnt(8)
	s_waitcnt lgkmcnt(0)
	s_barrier
	s_setprio 1
	s_waitcnt lgkmcnt(0)
	v_mfma_f32_16x16x32_bf16 v[62:65], v[140:143], v[176:179], v[62:65]
	v_mfma_f32_16x16x32_bf16 v[58:61], v[152:155], v[176:179], v[58:61]
	v_mfma_f32_16x16x32_bf16 v[54:57], v[140:143], v[184:187], v[54:57]
	v_mfma_f32_16x16x32_bf16 v[46:49], v[152:155], v[184:187], v[46:49]
	v_mfma_f32_16x16x32_bf16 v[38:41], v[140:143], v[192:195], v[38:41]
	v_mfma_f32_16x16x32_bf16 v[30:33], v[152:155], v[192:195], v[30:33]
	v_mfma_f32_16x16x32_bf16 v[22:25], v[140:143], v[200:203], v[22:25]
	v_mfma_f32_16x16x32_bf16 v[14:17], v[152:155], v[200:203], v[14:17]
	v_mfma_f32_16x16x32_bf16 v[62:65], v[148:151], v[180:183], v[62:65]
	v_mfma_f32_16x16x32_bf16 v[58:61], v[156:159], v[180:183], v[58:61]
	v_mfma_f32_16x16x32_bf16 v[54:57], v[148:151], v[188:191], v[54:57]
	v_mfma_f32_16x16x32_bf16 v[46:49], v[156:159], v[188:191], v[46:49]
	v_mfma_f32_16x16x32_bf16 v[38:41], v[148:151], v[196:199], v[38:41]
	v_mfma_f32_16x16x32_bf16 v[30:33], v[156:159], v[196:199], v[30:33]
	v_mfma_f32_16x16x32_bf16 v[22:25], v[148:151], v[204:207], v[22:25]
	v_mfma_f32_16x16x32_bf16 v[14:17], v[156:159], v[204:207], v[14:17]
	v_mfma_f32_16x16x32_bf16 v[50:53], v[160:163], v[176:179], v[50:53]
	v_mfma_f32_16x16x32_bf16 v[42:45], v[168:171], v[176:179], v[42:45]
	v_mfma_f32_16x16x32_bf16 v[34:37], v[160:163], v[184:187], v[34:37]
	v_mfma_f32_16x16x32_bf16 v[26:29], v[168:171], v[184:187], v[26:29]
	v_mfma_f32_16x16x32_bf16 v[18:21], v[160:163], v[192:195], v[18:21]
	v_mfma_f32_16x16x32_bf16 v[10:13], v[168:171], v[192:195], v[10:13]
	v_mfma_f32_16x16x32_bf16 v[6:9], v[160:163], v[200:203], v[6:9]
	v_mfma_f32_16x16x32_bf16 v[2:5], v[168:171], v[200:203], v[2:5]
	v_mfma_f32_16x16x32_bf16 v[50:53], v[164:167], v[180:183], v[50:53]
	v_mfma_f32_16x16x32_bf16 v[42:45], v[172:175], v[180:183], v[42:45]
	v_mfma_f32_16x16x32_bf16 v[34:37], v[164:167], v[188:191], v[34:37]
	v_mfma_f32_16x16x32_bf16 v[26:29], v[172:175], v[188:191], v[26:29]
	v_mfma_f32_16x16x32_bf16 v[18:21], v[164:167], v[196:199], v[18:21]
	v_mfma_f32_16x16x32_bf16 v[10:13], v[172:175], v[196:199], v[10:13]
	v_mfma_f32_16x16x32_bf16 v[6:9], v[164:167], v[204:207], v[6:9]
	s_barrier
	v_mfma_f32_16x16x32_bf16 v[2:5], v[172:175], v[204:207], v[2:5]
	s_setprio 0
	s_add_i32 s59, s59, 2
	s_add_u32 s30, s30, 0x100
	s_addc_u32 s31, s31, 0
	s_add_u32 s68, s68, 0x100
	s_addc_u32 s69, s69, 0
	s_cmp_gt_u32 s59, 13
	s_cbranch_scc0 .LBB0_489
	s_and_b64 vcc, exec, s[20:21]
	s_cbranch_vccz .LBB0_492
	s_barrier
